# prologue weight transposes: all 32 row loads of an item in flight before the LDS writes (was 4 batches of 8 with a drain each); on top of the passC fixes
# speedup vs baseline: 1.0087x; 1.0003x over previous
.LBB0_34:
	s_cmpk_gt_i32 s53, 0x57f
	s_mov_b64 s[22:23], -1
	s_cbranch_scc0 .LBB0_74
	s_cmpk_gt_u32 s53, 0xaff
	s_cbranch_scc0 .LBB0_69
	s_lshl_b32 s6, s52, 2
	s_and_b32 s24, s6, 0xf80
	s_cmpk_gt_u32 s53, 0x107f
	s_cbranch_scc0 .LBB0_64
	s_cmpk_gt_u32 s53, 0x15ff
	s_cbranch_scc0 .LBB0_59
	s_cmpk_gt_u32 s53, 0x1b7f
	s_cbranch_scc0 .LBB0_54
	s_cmpk_gt_u32 s53, 0x20ff
	s_cbranch_scc0 .LBB0_49
	s_cmpk_gt_u32 s53, 0x23ff
	s_cbranch_scc0 .LBB0_44
	s_and_b32 s6, s49, 0x1c0
	v_or_b32_e32 v4, s6, v60
	v_lshl_or_b32 v4, v4, 12, s24
	v_lshl_add_u64 v[38:39], v[20:21], 0, v[4:5]
	v_or_b32_e32 v4, s6, v61
	v_lshl_or_b32 v4, v4, 12, s24
	v_lshl_add_u64 v[40:41], v[20:21], 0, v[4:5]
	v_or_b32_e32 v4, s6, v62
	v_lshl_or_b32 v4, v4, 12, s24
	v_lshl_add_u64 v[42:43], v[20:21], 0, v[4:5]
	v_or_b32_e32 v4, s6, v63
	v_lshl_or_b32 v4, v4, 12, s24
	v_lshl_add_u64 v[44:45], v[20:21], 0, v[4:5]
	v_or_b32_e32 v4, s6, v64
	v_lshl_or_b32 v4, v4, 12, s24
	v_lshl_add_u64 v[46:47], v[20:21], 0, v[4:5]
	v_or_b32_e32 v4, s6, v65
	v_lshl_or_b32 v4, v4, 12, s24
	v_lshl_add_u64 v[48:49], v[20:21], 0, v[4:5]
	v_or_b32_e32 v4, s6, v66
	v_lshl_or_b32 v4, v4, 12, s24
	v_lshl_add_u64 v[50:51], v[20:21], 0, v[4:5]
	v_or_b32_e32 v4, s6, v3
	v_lshl_or_b32 v4, v4, 12, s24
	v_lshl_add_u64 v[52:53], v[20:21], 0, v[4:5]
	s_mov_b64 s[22:23], 0
	v_mov_b32_e32 v4, v59
	v_lshl_add_u64 v[68:69], v[52:53], 0, s[22:23]
	v_lshl_add_u64 v[70:71], v[50:51], 0, s[22:23]
	v_lshl_add_u64 v[72:73], v[48:49], 0, s[22:23]
	v_lshl_add_u64 v[74:75], v[46:47], 0, s[22:23]
	v_lshl_add_u64 v[76:77], v[44:45], 0, s[22:23]
	v_lshl_add_u64 v[78:79], v[42:43], 0, s[22:23]
	v_lshl_add_u64 v[80:81], v[40:41], 0, s[22:23]
	v_lshl_add_u64 v[82:83], v[38:39], 0, s[22:23]
	global_load_dword v100, v[68:69], off nt
	s_nop 0
	global_load_dword v101, v[70:71], off nt
	global_load_dword v102, v[72:73], off nt
	s_nop 0
	global_load_dword v103, v[74:75], off nt
	global_load_dword v104, v[76:77], off nt
	global_load_dword v105, v[78:79], off nt
	global_load_dword v106, v[80:81], off nt
	s_nop 0
	global_load_dword v107, v[82:83], off nt
	s_add_u32 s22, s22, 0x10000
	s_addc_u32 s23, s23, 0
	v_lshl_add_u64 v[68:69], v[52:53], 0, s[22:23]
	v_lshl_add_u64 v[70:71], v[50:51], 0, s[22:23]
	v_lshl_add_u64 v[72:73], v[48:49], 0, s[22:23]
	v_lshl_add_u64 v[74:75], v[46:47], 0, s[22:23]
	v_lshl_add_u64 v[76:77], v[44:45], 0, s[22:23]
	v_lshl_add_u64 v[78:79], v[42:43], 0, s[22:23]
	v_lshl_add_u64 v[80:81], v[40:41], 0, s[22:23]
	v_lshl_add_u64 v[82:83], v[38:39], 0, s[22:23]
	global_load_dword v108, v[68:69], off nt
	s_nop 0
	global_load_dword v109, v[70:71], off nt
	global_load_dword v110, v[72:73], off nt
	s_nop 0
	global_load_dword v111, v[74:75], off nt
	global_load_dword v112, v[76:77], off nt
	global_load_dword v113, v[78:79], off nt
	global_load_dword v114, v[80:81], off nt
	s_nop 0
	global_load_dword v115, v[82:83], off nt
	s_add_u32 s22, s22, 0x10000
	s_addc_u32 s23, s23, 0
	v_lshl_add_u64 v[68:69], v[52:53], 0, s[22:23]
	v_lshl_add_u64 v[70:71], v[50:51], 0, s[22:23]
	v_lshl_add_u64 v[72:73], v[48:49], 0, s[22:23]
	v_lshl_add_u64 v[74:75], v[46:47], 0, s[22:23]
	v_lshl_add_u64 v[76:77], v[44:45], 0, s[22:23]
	v_lshl_add_u64 v[78:79], v[42:43], 0, s[22:23]
	v_lshl_add_u64 v[80:81], v[40:41], 0, s[22:23]
	v_lshl_add_u64 v[82:83], v[38:39], 0, s[22:23]
	global_load_dword v116, v[68:69], off nt
	s_nop 0
	global_load_dword v117, v[70:71], off nt
	global_load_dword v118, v[72:73], off nt
	s_nop 0
	global_load_dword v119, v[74:75], off nt
	global_load_dword v120, v[76:77], off nt
	global_load_dword v121, v[78:79], off nt
	global_load_dword v122, v[80:81], off nt
	s_nop 0
	global_load_dword v123, v[82:83], off nt
	s_add_u32 s22, s22, 0x10000
	s_addc_u32 s23, s23, 0
	v_lshl_add_u64 v[68:69], v[52:53], 0, s[22:23]
	v_lshl_add_u64 v[70:71], v[50:51], 0, s[22:23]
	v_lshl_add_u64 v[72:73], v[48:49], 0, s[22:23]
	v_lshl_add_u64 v[74:75], v[46:47], 0, s[22:23]
	v_lshl_add_u64 v[76:77], v[44:45], 0, s[22:23]
	v_lshl_add_u64 v[78:79], v[42:43], 0, s[22:23]
	v_lshl_add_u64 v[80:81], v[40:41], 0, s[22:23]
	v_lshl_add_u64 v[82:83], v[38:39], 0, s[22:23]
	global_load_dword v124, v[68:69], off nt
	s_nop 0
	global_load_dword v125, v[70:71], off nt
	global_load_dword v126, v[72:73], off nt
	s_nop 0
	global_load_dword v127, v[74:75], off nt
	global_load_dword v128, v[76:77], off nt
	global_load_dword v129, v[78:79], off nt
	global_load_dword v130, v[80:81], off nt
	s_nop 0
	global_load_dword v131, v[82:83], off nt
	s_add_u32 s22, s22, 0x10000
	s_addc_u32 s23, s23, 0
	v_add_u32_e32 v75, 0x400, v4
	s_waitcnt vmcnt(30)
	ds_write2_b32 v4, v100, v101 offset1:66
	s_waitcnt vmcnt(28)
	ds_write2_b32 v4, v102, v103 offset0:132 offset1:198
	s_waitcnt vmcnt(26)
	ds_write2_b32 v75, v104, v105 offset0:8 offset1:74
	s_waitcnt vmcnt(24)
	ds_write2_b32 v75, v106, v107 offset0:140 offset1:206
	v_add_u32_e32 v4, 0x840, v4
	v_add_u32_e32 v75, 0x400, v4
	s_waitcnt vmcnt(22)
	ds_write2_b32 v4, v108, v109 offset1:66
	s_waitcnt vmcnt(20)
	ds_write2_b32 v4, v110, v111 offset0:132 offset1:198
	s_waitcnt vmcnt(18)
	ds_write2_b32 v75, v112, v113 offset0:8 offset1:74
	s_waitcnt vmcnt(16)
	ds_write2_b32 v75, v114, v115 offset0:140 offset1:206
	v_add_u32_e32 v4, 0x840, v4
	v_add_u32_e32 v75, 0x400, v4
	s_waitcnt vmcnt(14)
	ds_write2_b32 v4, v116, v117 offset1:66
	s_waitcnt vmcnt(12)
	ds_write2_b32 v4, v118, v119 offset0:132 offset1:198
	s_waitcnt vmcnt(10)
	ds_write2_b32 v75, v120, v121 offset0:8 offset1:74
	s_waitcnt vmcnt(8)
	ds_write2_b32 v75, v122, v123 offset0:140 offset1:206
	v_add_u32_e32 v4, 0x840, v4
	v_add_u32_e32 v75, 0x400, v4
	s_waitcnt vmcnt(6)
	ds_write2_b32 v4, v124, v125 offset1:66
	s_waitcnt vmcnt(4)
	ds_write2_b32 v4, v126, v127 offset0:132 offset1:198
	s_waitcnt vmcnt(2)
	ds_write2_b32 v75, v128, v129 offset0:8 offset1:74
	s_waitcnt vmcnt(0)
	ds_write2_b32 v75, v130, v131 offset0:140 offset1:206
	v_add_u32_e32 v4, 0x840, v4
	s_waitcnt lgkmcnt(0)
	ds_read2_b32 v[42:43], v55 offset1:8
	ds_read2_b32 v[46:47], v55 offset0:33 offset1:41
	ds_read2_b32 v[48:49], v55 offset0:66 offset1:74
	ds_read2_b32 v[50:51], v55 offset0:99 offset1:107
	ds_read2_b32 v[52:53], v55 offset0:132 offset1:140
	s_waitcnt lgkmcnt(4)
	v_bfe_u32 v4, v42, 16, 1
	v_add3_u32 v4, v42, v4, s42
	s_waitcnt lgkmcnt(3)
	v_bfe_u32 v23, v46, 16, 1
	v_lshrrev_b32_e32 v4, 16, v4
	v_add3_u32 v23, v46, v23, s42
	ds_read2_b32 v[68:69], v55 offset0:165 offset1:173
	v_and_or_b32 v38, v23, s43, v4
	s_waitcnt lgkmcnt(3)
	v_bfe_u32 v4, v48, 16, 1
	v_add3_u32 v4, v48, v4, s42
	s_waitcnt lgkmcnt(2)
	v_bfe_u32 v23, v50, 16, 1
	ds_read2_b32 v[70:71], v55 offset0:198 offset1:206
	v_lshrrev_b32_e32 v4, 16, v4
	v_add3_u32 v23, v50, v23, s42
	ds_read2_b32 v[72:73], v55 offset0:231 offset1:239
	v_and_or_b32 v39, v23, s43, v4
	s_waitcnt lgkmcnt(3)
	v_bfe_u32 v4, v52, 16, 1
	v_add3_u32 v4, v52, v4, s42
	s_waitcnt lgkmcnt(2)
	v_bfe_u32 v23, v68, 16, 1
	v_lshrrev_b32_e32 v4, 16, v4
	v_add3_u32 v23, v68, v23, s42
	v_and_or_b32 v40, v23, s43, v4
	s_waitcnt lgkmcnt(1)
	v_bfe_u32 v4, v70, 16, 1
	s_lshl_b32 s6, s53, 5
	v_add3_u32 v4, v70, v4, s42
	s_waitcnt lgkmcnt(0)
	v_bfe_u32 v23, v72, 16, 1
	s_and_b32 s22, s6, 0x3e0
	s_lshl_b32 s6, s53, 2
	v_lshrrev_b32_e32 v4, 16, v4
	v_add3_u32 v23, v72, v23, s42
	s_and_b32 s6, s6, 0x380
	v_and_or_b32 v41, v23, s43, v4
	v_or_b32_e32 v4, s22, v54
	v_lshl_add_u64 v[44:45], v[26:27], 0, s[6:7]
	v_lshlrev_b32_e32 v4, 11, v4
	v_lshl_add_u64 v[74:75], v[44:45], 0, v[4:5]
	v_bfe_u32 v4, v43, 16, 1
	v_add3_u32 v4, v43, v4, s42
	v_bfe_u32 v23, v47, 16, 1
	v_lshrrev_b32_e32 v4, 16, v4
	v_add3_u32 v23, v47, v23, s42
	global_store_dwordx4 v[74:75], v[38:41], off
	ds_read2_b32 v[42:43], v55 offset0:16 offset1:24
	s_nop 0
	v_and_or_b32 v38, v23, s43, v4
	v_bfe_u32 v4, v49, 16, 1
	v_add3_u32 v4, v49, v4, s42
	v_bfe_u32 v23, v51, 16, 1
	v_lshrrev_b32_e32 v4, 16, v4
	v_add3_u32 v23, v51, v23, s42
	v_and_or_b32 v39, v23, s43, v4
	v_bfe_u32 v4, v53, 16, 1
	v_add3_u32 v4, v53, v4, s42
	v_bfe_u32 v23, v69, 16, 1
	v_lshrrev_b32_e32 v4, 16, v4
	v_add3_u32 v23, v69, v23, s42
	v_and_or_b32 v40, v23, s43, v4
	v_bfe_u32 v4, v71, 16, 1
	v_add3_u32 v4, v71, v4, s42
	v_bfe_u32 v23, v73, 16, 1
	v_lshrrev_b32_e32 v4, 16, v4
	v_add3_u32 v23, v73, v23, s42
	v_and_or_b32 v41, v23, s43, v4
	v_or_b32_e32 v4, s22, v56
	v_lshlrev_b32_e32 v4, 11, v4
	v_lshl_add_u64 v[46:47], v[44:45], 0, v[4:5]
	global_store_dwordx4 v[46:47], v[38:41], off
	ds_read2_b32 v[46:47], v55 offset0:49 offset1:57
	ds_read2_b32 v[48:49], v55 offset0:82 offset1:90
	ds_read2_b32 v[50:51], v55 offset0:115 offset1:123
	s_waitcnt lgkmcnt(3)
	v_bfe_u32 v4, v42, 16, 1
	v_add3_u32 v4, v42, v4, s42
	s_waitcnt lgkmcnt(2)
	v_bfe_u32 v23, v46, 16, 1
	ds_read2_b32 v[52:53], v55 offset0:148 offset1:156
	v_lshrrev_b32_e32 v4, 16, v4
	v_add3_u32 v23, v46, v23, s42
	ds_read2_b32 v[68:69], v55 offset0:181 offset1:189
	v_and_or_b32 v38, v23, s43, v4
	s_waitcnt lgkmcnt(3)
	v_bfe_u32 v4, v48, 16, 1
	v_add3_u32 v4, v48, v4, s42
	s_waitcnt lgkmcnt(2)
	v_bfe_u32 v23, v50, 16, 1
	ds_read2_b32 v[70:71], v55 offset0:214 offset1:222
	v_lshrrev_b32_e32 v4, 16, v4
	v_add3_u32 v23, v50, v23, s42
	ds_read2_b32 v[72:73], v55 offset0:247 offset1:255
	v_and_or_b32 v39, v23, s43, v4
	s_waitcnt lgkmcnt(3)
	v_bfe_u32 v4, v52, 16, 1
	v_add3_u32 v4, v52, v4, s42
	s_waitcnt lgkmcnt(2)
	v_bfe_u32 v23, v68, 16, 1
	v_lshrrev_b32_e32 v4, 16, v4
	v_add3_u32 v23, v68, v23, s42
	v_and_or_b32 v40, v23, s43, v4
	s_waitcnt lgkmcnt(1)
	v_bfe_u32 v4, v70, 16, 1
	v_add3_u32 v4, v70, v4, s42
	s_waitcnt lgkmcnt(0)
	v_bfe_u32 v23, v72, 16, 1
	v_lshrrev_b32_e32 v4, 16, v4
	v_add3_u32 v23, v72, v23, s42
	v_and_or_b32 v41, v23, s43, v4
	v_or_b32_e32 v4, s22, v57
	v_lshlrev_b32_e32 v4, 11, v4
	v_lshl_add_u64 v[74:75], v[44:45], 0, v[4:5]
	v_bfe_u32 v4, v43, 16, 1
	v_add3_u32 v4, v43, v4, s42
	v_bfe_u32 v23, v47, 16, 1
	v_lshrrev_b32_e32 v4, 16, v4
	v_add3_u32 v23, v47, v23, s42
	global_store_dwordx4 v[74:75], v[38:41], off
	s_nop 1
	v_and_or_b32 v38, v23, s43, v4
	v_bfe_u32 v4, v49, 16, 1
	v_add3_u32 v4, v49, v4, s42
	v_bfe_u32 v23, v51, 16, 1
	v_lshrrev_b32_e32 v4, 16, v4
	v_add3_u32 v23, v51, v23, s42
	v_and_or_b32 v39, v23, s43, v4
	v_bfe_u32 v4, v53, 16, 1
	v_add3_u32 v4, v53, v4, s42
	v_bfe_u32 v23, v69, 16, 1
	v_lshrrev_b32_e32 v4, 16, v4
	v_add3_u32 v23, v69, v23, s42
	v_and_or_b32 v40, v23, s43, v4
	v_bfe_u32 v4, v71, 16, 1
	v_add3_u32 v4, v71, v4, s42
	v_bfe_u32 v23, v73, 16, 1
	v_lshrrev_b32_e32 v4, 16, v4
	v_add3_u32 v23, v73, v23, s42
	v_and_or_b32 v41, v23, s43, v4
	v_or_b32_e32 v4, s22, v58
	v_lshlrev_b32_e32 v4, 11, v4
	v_lshl_add_u64 v[42:43], v[44:45], 0, v[4:5]
	global_store_dwordx4 v[42:43], v[38:41], off
	s_waitcnt lgkmcnt(0)
	s_mov_b64 s[22:23], 0
.LBB0_44:
	s_and_b64 vcc, exec, s[22:23]
	s_cbranch_vccz .LBB0_48
	s_add_i32 s6, s53, 0xdf00
	s_and_b32 s22, s6, 0xffff
	s_mul_i32 s22, s22, 0xaaab
	s_lshr_b32 s22, s22, 21
	s_mul_i32 s23, s22, 48
	s_sub_i32 s6, s6, s23
	s_lshl_b32 s25, s22, 6
	s_lshl_b32 s54, s6, 5
	s_lshl_b32 s6, s6, 7
	v_or_b32_e32 v4, s25, v60
	s_and_b32 s6, s6, 0x3ff80
	v_mul_u32_u24_e32 v4, 0x1800, v4
	v_lshl_add_u64 v[38:39], s[6:7], 0, v[4:5]
	v_or_b32_e32 v4, s25, v61
	v_mul_u32_u24_e32 v4, 0x1800, v4
	v_lshl_add_u64 v[40:41], s[6:7], 0, v[4:5]
	v_or_b32_e32 v4, s25, v62
	v_mul_u32_u24_e32 v4, 0x1800, v4
	v_lshl_add_u64 v[42:43], s[6:7], 0, v[4:5]
	v_or_b32_e32 v4, s25, v63
	v_mul_u32_u24_e32 v4, 0x1800, v4
	v_lshl_add_u64 v[44:45], s[6:7], 0, v[4:5]
	v_or_b32_e32 v4, s25, v64
	v_mul_u32_u24_e32 v4, 0x1800, v4
	v_lshl_add_u64 v[46:47], s[6:7], 0, v[4:5]
	v_or_b32_e32 v4, s25, v65
	v_mul_u32_u24_e32 v4, 0x1800, v4
	v_lshl_add_u64 v[48:49], s[6:7], 0, v[4:5]
	v_or_b32_e32 v4, s25, v66
	v_mul_u32_u24_e32 v4, 0x1800, v4
	v_lshl_add_u64 v[50:51], s[6:7], 0, v[4:5]
	v_or_b32_e32 v4, s25, v3
	v_mov_b64_e32 v[52:53], s[6:7]
	v_mad_u64_u32 v[52:53], s[22:23], v4, s44, v[52:53]
	v_lshl_add_u64 v[38:39], v[6:7], 0, v[38:39]
	v_lshl_add_u64 v[40:41], v[6:7], 0, v[40:41]
	v_lshl_add_u64 v[42:43], v[6:7], 0, v[42:43]
	v_lshl_add_u64 v[44:45], v[6:7], 0, v[44:45]
	v_lshl_add_u64 v[46:47], v[6:7], 0, v[46:47]
	v_lshl_add_u64 v[48:49], v[6:7], 0, v[48:49]
	v_lshl_add_u64 v[50:51], v[6:7], 0, v[50:51]
	v_lshl_add_u64 v[52:53], v[6:7], 0, v[52:53]
	s_mov_b64 s[22:23], 0
	v_mov_b32_e32 v4, v59
	v_lshl_add_u64 v[68:69], v[52:53], 0, s[22:23]
	v_lshl_add_u64 v[70:71], v[50:51], 0, s[22:23]
	v_lshl_add_u64 v[72:73], v[48:49], 0, s[22:23]
	v_lshl_add_u64 v[74:75], v[46:47], 0, s[22:23]
	v_lshl_add_u64 v[76:77], v[44:45], 0, s[22:23]
	v_lshl_add_u64 v[78:79], v[42:43], 0, s[22:23]
	v_lshl_add_u64 v[80:81], v[40:41], 0, s[22:23]
	v_lshl_add_u64 v[82:83], v[38:39], 0, s[22:23]
	global_load_dword v100, v[68:69], off nt
	s_nop 0
	global_load_dword v101, v[70:71], off nt
	global_load_dword v102, v[72:73], off nt
	s_nop 0
	global_load_dword v103, v[74:75], off nt
	global_load_dword v104, v[76:77], off nt
	global_load_dword v105, v[78:79], off nt
	global_load_dword v106, v[80:81], off nt
	s_nop 0
	global_load_dword v107, v[82:83], off nt
	s_add_u32 s22, s22, 0x18000
	s_addc_u32 s23, s23, 0
	v_lshl_add_u64 v[68:69], v[52:53], 0, s[22:23]
	v_lshl_add_u64 v[70:71], v[50:51], 0, s[22:23]
	v_lshl_add_u64 v[72:73], v[48:49], 0, s[22:23]
	v_lshl_add_u64 v[74:75], v[46:47], 0, s[22:23]
	v_lshl_add_u64 v[76:77], v[44:45], 0, s[22:23]
	v_lshl_add_u64 v[78:79], v[42:43], 0, s[22:23]
	v_lshl_add_u64 v[80:81], v[40:41], 0, s[22:23]
	v_lshl_add_u64 v[82:83], v[38:39], 0, s[22:23]
	global_load_dword v108, v[68:69], off nt
	s_nop 0
	global_load_dword v109, v[70:71], off nt
	global_load_dword v110, v[72:73], off nt
	s_nop 0
	global_load_dword v111, v[74:75], off nt
	global_load_dword v112, v[76:77], off nt
	global_load_dword v113, v[78:79], off nt
	global_load_dword v114, v[80:81], off nt
	s_nop 0
	global_load_dword v115, v[82:83], off nt
	s_add_u32 s22, s22, 0x18000
	s_addc_u32 s23, s23, 0
	v_lshl_add_u64 v[68:69], v[52:53], 0, s[22:23]
	v_lshl_add_u64 v[70:71], v[50:51], 0, s[22:23]
	v_lshl_add_u64 v[72:73], v[48:49], 0, s[22:23]
	v_lshl_add_u64 v[74:75], v[46:47], 0, s[22:23]
	v_lshl_add_u64 v[76:77], v[44:45], 0, s[22:23]
	v_lshl_add_u64 v[78:79], v[42:43], 0, s[22:23]
	v_lshl_add_u64 v[80:81], v[40:41], 0, s[22:23]
	v_lshl_add_u64 v[82:83], v[38:39], 0, s[22:23]
	global_load_dword v116, v[68:69], off nt
	s_nop 0
	global_load_dword v117, v[70:71], off nt
	global_load_dword v118, v[72:73], off nt
	s_nop 0
	global_load_dword v119, v[74:75], off nt
	global_load_dword v120, v[76:77], off nt
	global_load_dword v121, v[78:79], off nt
	global_load_dword v122, v[80:81], off nt
	s_nop 0
	global_load_dword v123, v[82:83], off nt
	s_add_u32 s22, s22, 0x18000
	s_addc_u32 s23, s23, 0
	v_lshl_add_u64 v[68:69], v[52:53], 0, s[22:23]
	v_lshl_add_u64 v[70:71], v[50:51], 0, s[22:23]
	v_lshl_add_u64 v[72:73], v[48:49], 0, s[22:23]
	v_lshl_add_u64 v[74:75], v[46:47], 0, s[22:23]
	v_lshl_add_u64 v[76:77], v[44:45], 0, s[22:23]
	v_lshl_add_u64 v[78:79], v[42:43], 0, s[22:23]
	v_lshl_add_u64 v[80:81], v[40:41], 0, s[22:23]
	v_lshl_add_u64 v[82:83], v[38:39], 0, s[22:23]
	global_load_dword v124, v[68:69], off nt
	s_nop 0
	global_load_dword v125, v[70:71], off nt
	global_load_dword v126, v[72:73], off nt
	s_nop 0
	global_load_dword v127, v[74:75], off nt
	global_load_dword v128, v[76:77], off nt
	global_load_dword v129, v[78:79], off nt
	global_load_dword v130, v[80:81], off nt
	s_nop 0
	global_load_dword v131, v[82:83], off nt
	s_add_u32 s22, s22, 0x18000
	s_addc_u32 s23, s23, 0
	v_add_u32_e32 v75, 0x400, v4
	s_waitcnt vmcnt(30)
	ds_write2_b32 v4, v100, v101 offset1:66
	s_waitcnt vmcnt(28)
	ds_write2_b32 v4, v102, v103 offset0:132 offset1:198
	s_waitcnt vmcnt(26)
	ds_write2_b32 v75, v104, v105 offset0:8 offset1:74
	s_waitcnt vmcnt(24)
	ds_write2_b32 v75, v106, v107 offset0:140 offset1:206
	v_add_u32_e32 v4, 0x840, v4
	v_add_u32_e32 v75, 0x400, v4
	s_waitcnt vmcnt(22)
	ds_write2_b32 v4, v108, v109 offset1:66
	s_waitcnt vmcnt(20)
	ds_write2_b32 v4, v110, v111 offset0:132 offset1:198
	s_waitcnt vmcnt(18)
	ds_write2_b32 v75, v112, v113 offset0:8 offset1:74
	s_waitcnt vmcnt(16)
	ds_write2_b32 v75, v114, v115 offset0:140 offset1:206
	v_add_u32_e32 v4, 0x840, v4
	v_add_u32_e32 v75, 0x400, v4
	s_waitcnt vmcnt(14)
	ds_write2_b32 v4, v116, v117 offset1:66
	s_waitcnt vmcnt(12)
	ds_write2_b32 v4, v118, v119 offset0:132 offset1:198
	s_waitcnt vmcnt(10)
	ds_write2_b32 v75, v120, v121 offset0:8 offset1:74
	s_waitcnt vmcnt(8)
	ds_write2_b32 v75, v122, v123 offset0:140 offset1:206
	v_add_u32_e32 v4, 0x840, v4
	v_add_u32_e32 v75, 0x400, v4
	s_waitcnt vmcnt(6)
	ds_write2_b32 v4, v124, v125 offset1:66
	s_waitcnt vmcnt(4)
	ds_write2_b32 v4, v126, v127 offset0:132 offset1:198
	s_waitcnt vmcnt(2)
	ds_write2_b32 v75, v128, v129 offset0:8 offset1:74
	s_waitcnt vmcnt(0)
	ds_write2_b32 v75, v130, v131 offset0:140 offset1:206
	v_add_u32_e32 v4, 0x840, v4
	s_waitcnt lgkmcnt(0)
	ds_read2_b32 v[42:43], v55 offset1:8
	ds_read2_b32 v[46:47], v55 offset0:33 offset1:41
	ds_read2_b32 v[48:49], v55 offset0:66 offset1:74
	ds_read2_b32 v[50:51], v55 offset0:99 offset1:107
	ds_read2_b32 v[52:53], v55 offset0:132 offset1:140
	s_waitcnt lgkmcnt(4)
	v_bfe_u32 v4, v42, 16, 1
	v_add3_u32 v4, v42, v4, s42
	s_waitcnt lgkmcnt(3)
	v_bfe_u32 v23, v46, 16, 1
	v_lshrrev_b32_e32 v4, 16, v4
	v_add3_u32 v23, v46, v23, s42
	ds_read2_b32 v[68:69], v55 offset0:165 offset1:173
	v_and_or_b32 v38, v23, s43, v4
	s_waitcnt lgkmcnt(3)
	v_bfe_u32 v4, v48, 16, 1
	v_add3_u32 v4, v48, v4, s42
	s_waitcnt lgkmcnt(2)
	v_bfe_u32 v23, v50, 16, 1
	ds_read2_b32 v[70:71], v55 offset0:198 offset1:206
	v_lshrrev_b32_e32 v4, 16, v4
	v_add3_u32 v23, v50, v23, s42
	ds_read2_b32 v[72:73], v55 offset0:231 offset1:239
	v_and_or_b32 v39, v23, s43, v4
	s_waitcnt lgkmcnt(3)
	v_bfe_u32 v4, v52, 16, 1
	v_add3_u32 v4, v52, v4, s42
	s_waitcnt lgkmcnt(2)
	v_bfe_u32 v23, v68, 16, 1
	v_lshrrev_b32_e32 v4, 16, v4
	v_add3_u32 v23, v68, v23, s42
	v_and_or_b32 v40, v23, s43, v4
	s_waitcnt lgkmcnt(1)
	v_bfe_u32 v4, v70, 16, 1
	v_add3_u32 v4, v70, v4, s42
	s_waitcnt lgkmcnt(0)
	v_bfe_u32 v23, v72, 16, 1
	s_and_b32 s22, 0xffff, s54
	v_lshrrev_b32_e32 v4, 16, v4
	v_add3_u32 v23, v72, v23, s42
	s_lshl_b32 s6, s25, 1
	v_and_or_b32 v41, v23, s43, v4
	v_or_b32_e32 v4, s22, v54
	v_lshl_add_u64 v[44:45], v[28:29], 0, s[6:7]
	v_lshlrev_b32_e32 v4, 11, v4
	v_lshl_add_u64 v[74:75], v[44:45], 0, v[4:5]
	v_bfe_u32 v4, v43, 16, 1
	v_add3_u32 v4, v43, v4, s42
	v_bfe_u32 v23, v47, 16, 1
	v_lshrrev_b32_e32 v4, 16, v4
	v_add3_u32 v23, v47, v23, s42
	global_store_dwordx4 v[74:75], v[38:41], off
	ds_read2_b32 v[42:43], v55 offset0:16 offset1:24
	s_nop 0
	v_and_or_b32 v38, v23, s43, v4
	v_bfe_u32 v4, v49, 16, 1
	v_add3_u32 v4, v49, v4, s42
	v_bfe_u32 v23, v51, 16, 1
	v_lshrrev_b32_e32 v4, 16, v4
	v_add3_u32 v23, v51, v23, s42
	v_and_or_b32 v39, v23, s43, v4
	v_bfe_u32 v4, v53, 16, 1
	v_add3_u32 v4, v53, v4, s42
	v_bfe_u32 v23, v69, 16, 1
	v_lshrrev_b32_e32 v4, 16, v4
	v_add3_u32 v23, v69, v23, s42
	v_and_or_b32 v40, v23, s43, v4
	v_bfe_u32 v4, v71, 16, 1
	v_add3_u32 v4, v71, v4, s42
	v_bfe_u32 v23, v73, 16, 1
	v_lshrrev_b32_e32 v4, 16, v4
	v_add3_u32 v23, v73, v23, s42
	v_and_or_b32 v41, v23, s43, v4
	v_or_b32_e32 v4, s22, v56
	v_lshlrev_b32_e32 v4, 11, v4
	v_lshl_add_u64 v[46:47], v[44:45], 0, v[4:5]
	global_store_dwordx4 v[46:47], v[38:41], off
	ds_read2_b32 v[46:47], v55 offset0:49 offset1:57
	ds_read2_b32 v[48:49], v55 offset0:82 offset1:90
	ds_read2_b32 v[50:51], v55 offset0:115 offset1:123
	s_waitcnt lgkmcnt(3)
	v_bfe_u32 v4, v42, 16, 1
	v_add3_u32 v4, v42, v4, s42
	s_waitcnt lgkmcnt(2)
	v_bfe_u32 v23, v46, 16, 1
	ds_read2_b32 v[52:53], v55 offset0:148 offset1:156
	v_lshrrev_b32_e32 v4, 16, v4
	v_add3_u32 v23, v46, v23, s42
	ds_read2_b32 v[68:69], v55 offset0:181 offset1:189
	v_and_or_b32 v38, v23, s43, v4
	s_waitcnt lgkmcnt(3)
	v_bfe_u32 v4, v48, 16, 1
	v_add3_u32 v4, v48, v4, s42
	s_waitcnt lgkmcnt(2)
	v_bfe_u32 v23, v50, 16, 1
	ds_read2_b32 v[70:71], v55 offset0:214 offset1:222
	v_lshrrev_b32_e32 v4, 16, v4
	v_add3_u32 v23, v50, v23, s42
	ds_read2_b32 v[72:73], v55 offset0:247 offset1:255
	v_and_or_b32 v39, v23, s43, v4
	s_waitcnt lgkmcnt(3)
	v_bfe_u32 v4, v52, 16, 1
	v_add3_u32 v4, v52, v4, s42
	s_waitcnt lgkmcnt(2)
	v_bfe_u32 v23, v68, 16, 1
	v_lshrrev_b32_e32 v4, 16, v4
	v_add3_u32 v23, v68, v23, s42
	v_and_or_b32 v40, v23, s43, v4
	s_waitcnt lgkmcnt(1)
	v_bfe_u32 v4, v70, 16, 1
	v_add3_u32 v4, v70, v4, s42
	s_waitcnt lgkmcnt(0)
	v_bfe_u32 v23, v72, 16, 1
	v_lshrrev_b32_e32 v4, 16, v4
	v_add3_u32 v23, v72, v23, s42
	v_and_or_b32 v41, v23, s43, v4
	v_or_b32_e32 v4, s22, v57
	v_lshlrev_b32_e32 v4, 11, v4
	v_lshl_add_u64 v[74:75], v[44:45], 0, v[4:5]
	v_bfe_u32 v4, v43, 16, 1
	v_add3_u32 v4, v43, v4, s42
	v_bfe_u32 v23, v47, 16, 1
	v_lshrrev_b32_e32 v4, 16, v4
	v_add3_u32 v23, v47, v23, s42
	global_store_dwordx4 v[74:75], v[38:41], off
	s_nop 1
	v_and_or_b32 v38, v23, s43, v4
	v_bfe_u32 v4, v49, 16, 1
	v_add3_u32 v4, v49, v4, s42
	v_bfe_u32 v23, v51, 16, 1
	v_lshrrev_b32_e32 v4, 16, v4
	v_add3_u32 v23, v51, v23, s42
	v_and_or_b32 v39, v23, s43, v4
	v_bfe_u32 v4, v53, 16, 1
	v_add3_u32 v4, v53, v4, s42
	v_bfe_u32 v23, v69, 16, 1
	v_lshrrev_b32_e32 v4, 16, v4
	v_add3_u32 v23, v69, v23, s42
	v_and_or_b32 v40, v23, s43, v4
	v_bfe_u32 v4, v71, 16, 1
	v_add3_u32 v4, v71, v4, s42
	v_bfe_u32 v23, v73, 16, 1
	v_lshrrev_b32_e32 v4, 16, v4
	v_add3_u32 v23, v73, v23, s42
	v_and_or_b32 v41, v23, s43, v4
	v_or_b32_e32 v4, s22, v58
	v_lshlrev_b32_e32 v4, 11, v4
	v_lshl_add_u64 v[42:43], v[44:45], 0, v[4:5]
	global_store_dwordx4 v[42:43], v[38:41], off
	s_waitcnt lgkmcnt(0)

.LBB0_49:
	s_andn2_b64 vcc, exec, s[22:23]
	s_cbranch_vccnz .LBB0_53
	s_and_b32 s6, s48, 0x1ffc0
	v_or_b32_e32 v4, s6, v60
	v_lshl_or_b32 v4, v4, 12, s24
	v_lshl_add_u64 v[38:39], v[8:9], 0, v[4:5]
	v_or_b32_e32 v4, s6, v61
	v_lshl_or_b32 v4, v4, 12, s24
	v_lshl_add_u64 v[40:41], v[8:9], 0, v[4:5]
	v_or_b32_e32 v4, s6, v62
	v_lshl_or_b32 v4, v4, 12, s24
	v_lshl_add_u64 v[42:43], v[8:9], 0, v[4:5]
	v_or_b32_e32 v4, s6, v63
	v_lshl_or_b32 v4, v4, 12, s24
	v_lshl_add_u64 v[44:45], v[8:9], 0, v[4:5]
	v_or_b32_e32 v4, s6, v64
	v_lshl_or_b32 v4, v4, 12, s24
	v_lshl_add_u64 v[46:47], v[8:9], 0, v[4:5]
	v_or_b32_e32 v4, s6, v65
	v_lshl_or_b32 v4, v4, 12, s24
	v_lshl_add_u64 v[48:49], v[8:9], 0, v[4:5]
	v_or_b32_e32 v4, s6, v66
	v_lshl_or_b32 v4, v4, 12, s24
	v_lshl_add_u64 v[50:51], v[8:9], 0, v[4:5]
	v_or_b32_e32 v4, s6, v3
	v_lshl_or_b32 v4, v4, 12, s24
	v_lshl_add_u64 v[52:53], v[8:9], 0, v[4:5]
	s_mov_b64 s[22:23], 0
	v_mov_b32_e32 v4, v59
	v_lshl_add_u64 v[68:69], v[52:53], 0, s[22:23]
	v_lshl_add_u64 v[70:71], v[50:51], 0, s[22:23]
	v_lshl_add_u64 v[72:73], v[48:49], 0, s[22:23]
	v_lshl_add_u64 v[74:75], v[46:47], 0, s[22:23]
	v_lshl_add_u64 v[76:77], v[44:45], 0, s[22:23]
	v_lshl_add_u64 v[78:79], v[42:43], 0, s[22:23]
	v_lshl_add_u64 v[80:81], v[40:41], 0, s[22:23]
	v_lshl_add_u64 v[82:83], v[38:39], 0, s[22:23]
	global_load_dword v100, v[68:69], off nt
	s_nop 0
	global_load_dword v101, v[70:71], off nt
	global_load_dword v102, v[72:73], off nt
	s_nop 0
	global_load_dword v103, v[74:75], off nt
	global_load_dword v104, v[76:77], off nt
	global_load_dword v105, v[78:79], off nt
	global_load_dword v106, v[80:81], off nt
	s_nop 0
	global_load_dword v107, v[82:83], off nt
	s_add_u32 s22, s22, 0x10000
	s_addc_u32 s23, s23, 0
	v_lshl_add_u64 v[68:69], v[52:53], 0, s[22:23]
	v_lshl_add_u64 v[70:71], v[50:51], 0, s[22:23]
	v_lshl_add_u64 v[72:73], v[48:49], 0, s[22:23]
	v_lshl_add_u64 v[74:75], v[46:47], 0, s[22:23]
	v_lshl_add_u64 v[76:77], v[44:45], 0, s[22:23]
	v_lshl_add_u64 v[78:79], v[42:43], 0, s[22:23]
	v_lshl_add_u64 v[80:81], v[40:41], 0, s[22:23]
	v_lshl_add_u64 v[82:83], v[38:39], 0, s[22:23]
	global_load_dword v108, v[68:69], off nt
	s_nop 0
	global_load_dword v109, v[70:71], off nt
	global_load_dword v110, v[72:73], off nt
	s_nop 0
	global_load_dword v111, v[74:75], off nt
	global_load_dword v112, v[76:77], off nt
	global_load_dword v113, v[78:79], off nt
	global_load_dword v114, v[80:81], off nt
	s_nop 0
	global_load_dword v115, v[82:83], off nt
	s_add_u32 s22, s22, 0x10000
	s_addc_u32 s23, s23, 0
	v_lshl_add_u64 v[68:69], v[52:53], 0, s[22:23]
	v_lshl_add_u64 v[70:71], v[50:51], 0, s[22:23]
	v_lshl_add_u64 v[72:73], v[48:49], 0, s[22:23]
	v_lshl_add_u64 v[74:75], v[46:47], 0, s[22:23]
	v_lshl_add_u64 v[76:77], v[44:45], 0, s[22:23]
	v_lshl_add_u64 v[78:79], v[42:43], 0, s[22:23]
	v_lshl_add_u64 v[80:81], v[40:41], 0, s[22:23]
	v_lshl_add_u64 v[82:83], v[38:39], 0, s[22:23]
	global_load_dword v116, v[68:69], off nt
	s_nop 0
	global_load_dword v117, v[70:71], off nt
	global_load_dword v118, v[72:73], off nt
	s_nop 0
	global_load_dword v119, v[74:75], off nt
	global_load_dword v120, v[76:77], off nt
	global_load_dword v121, v[78:79], off nt
	global_load_dword v122, v[80:81], off nt
	s_nop 0
	global_load_dword v123, v[82:83], off nt
	s_add_u32 s22, s22, 0x10000
	s_addc_u32 s23, s23, 0
	v_lshl_add_u64 v[68:69], v[52:53], 0, s[22:23]
	v_lshl_add_u64 v[70:71], v[50:51], 0, s[22:23]
	v_lshl_add_u64 v[72:73], v[48:49], 0, s[22:23]
	v_lshl_add_u64 v[74:75], v[46:47], 0, s[22:23]
	v_lshl_add_u64 v[76:77], v[44:45], 0, s[22:23]
	v_lshl_add_u64 v[78:79], v[42:43], 0, s[22:23]
	v_lshl_add_u64 v[80:81], v[40:41], 0, s[22:23]
	v_lshl_add_u64 v[82:83], v[38:39], 0, s[22:23]
	global_load_dword v124, v[68:69], off nt
	s_nop 0
	global_load_dword v125, v[70:71], off nt
	global_load_dword v126, v[72:73], off nt
	s_nop 0
	global_load_dword v127, v[74:75], off nt
	global_load_dword v128, v[76:77], off nt
	global_load_dword v129, v[78:79], off nt
	global_load_dword v130, v[80:81], off nt
	s_nop 0
	global_load_dword v131, v[82:83], off nt
	s_add_u32 s22, s22, 0x10000
	s_addc_u32 s23, s23, 0
	v_add_u32_e32 v75, 0x400, v4
	s_waitcnt vmcnt(30)
	ds_write2_b32 v4, v100, v101 offset1:66
	s_waitcnt vmcnt(28)
	ds_write2_b32 v4, v102, v103 offset0:132 offset1:198
	s_waitcnt vmcnt(26)
	ds_write2_b32 v75, v104, v105 offset0:8 offset1:74
	s_waitcnt vmcnt(24)
	ds_write2_b32 v75, v106, v107 offset0:140 offset1:206
	v_add_u32_e32 v4, 0x840, v4
	v_add_u32_e32 v75, 0x400, v4
	s_waitcnt vmcnt(22)
	ds_write2_b32 v4, v108, v109 offset1:66
	s_waitcnt vmcnt(20)
	ds_write2_b32 v4, v110, v111 offset0:132 offset1:198
	s_waitcnt vmcnt(18)
	ds_write2_b32 v75, v112, v113 offset0:8 offset1:74
	s_waitcnt vmcnt(16)
	ds_write2_b32 v75, v114, v115 offset0:140 offset1:206
	v_add_u32_e32 v4, 0x840, v4
	v_add_u32_e32 v75, 0x400, v4
	s_waitcnt vmcnt(14)
	ds_write2_b32 v4, v116, v117 offset1:66
	s_waitcnt vmcnt(12)
	ds_write2_b32 v4, v118, v119 offset0:132 offset1:198
	s_waitcnt vmcnt(10)
	ds_write2_b32 v75, v120, v121 offset0:8 offset1:74
	s_waitcnt vmcnt(8)
	ds_write2_b32 v75, v122, v123 offset0:140 offset1:206
	v_add_u32_e32 v4, 0x840, v4
	v_add_u32_e32 v75, 0x400, v4
	s_waitcnt vmcnt(6)
	ds_write2_b32 v4, v124, v125 offset1:66
	s_waitcnt vmcnt(4)
	ds_write2_b32 v4, v126, v127 offset0:132 offset1:198
	s_waitcnt vmcnt(2)
	ds_write2_b32 v75, v128, v129 offset0:8 offset1:74
	s_waitcnt vmcnt(0)
	ds_write2_b32 v75, v130, v131 offset0:140 offset1:206
	v_add_u32_e32 v4, 0x840, v4
	s_waitcnt lgkmcnt(0)
	ds_read2_b32 v[42:43], v55 offset1:8
	ds_read2_b32 v[46:47], v55 offset0:33 offset1:41
	ds_read2_b32 v[48:49], v55 offset0:66 offset1:74
	ds_read2_b32 v[50:51], v55 offset0:99 offset1:107
	ds_read2_b32 v[52:53], v55 offset0:132 offset1:140
	s_waitcnt lgkmcnt(4)
	v_bfe_u32 v4, v42, 16, 1
	v_add3_u32 v4, v42, v4, s42
	s_waitcnt lgkmcnt(3)
	v_bfe_u32 v23, v46, 16, 1
	v_lshrrev_b32_e32 v4, 16, v4
	v_add3_u32 v23, v46, v23, s42
	ds_read2_b32 v[68:69], v55 offset0:165 offset1:173
	v_and_or_b32 v38, v23, s43, v4
	s_waitcnt lgkmcnt(3)
	v_bfe_u32 v4, v48, 16, 1
	v_add3_u32 v4, v48, v4, s42
	s_waitcnt lgkmcnt(2)
	v_bfe_u32 v23, v50, 16, 1
	ds_read2_b32 v[70:71], v55 offset0:198 offset1:206
	v_lshrrev_b32_e32 v4, 16, v4
	v_add3_u32 v23, v50, v23, s42
	ds_read2_b32 v[72:73], v55 offset0:231 offset1:239
	v_and_or_b32 v39, v23, s43, v4
	s_waitcnt lgkmcnt(3)
	v_bfe_u32 v4, v52, 16, 1
	v_add3_u32 v4, v52, v4, s42
	s_waitcnt lgkmcnt(2)
	v_bfe_u32 v23, v68, 16, 1
	v_lshrrev_b32_e32 v4, 16, v4
	v_add3_u32 v23, v68, v23, s42
	v_and_or_b32 v40, v23, s43, v4
	s_waitcnt lgkmcnt(1)
	v_bfe_u32 v4, v70, 16, 1
	s_lshl_b32 s6, s53, 1
	s_lshl_b32 s22, s53, 5
	v_add3_u32 v4, v70, v4, s42
	s_waitcnt lgkmcnt(0)
	v_bfe_u32 v23, v72, 16, 1
	s_add_i32 s6, s6, 0x1c900
	s_and_b32 s22, s22, 0x3e0
	v_lshrrev_b32_e32 v4, 16, v4
	v_add3_u32 v23, v72, v23, s42
	s_and_b32 s6, s6, 0x1ffc0
	v_and_or_b32 v41, v23, s43, v4
	v_or_b32_e32 v4, s22, v54
	s_lshl_b32 s6, s6, 1
	v_mul_u32_u24_e32 v4, 0xb00, v4
	v_lshl_add_u64 v[44:45], v[30:31], 0, s[6:7]
	v_lshlrev_b32_e32 v4, 1, v4
	v_lshl_add_u64 v[74:75], v[44:45], 0, v[4:5]
	v_bfe_u32 v4, v43, 16, 1
	v_add3_u32 v4, v43, v4, s42
	v_bfe_u32 v23, v47, 16, 1
	v_lshrrev_b32_e32 v4, 16, v4
	v_add3_u32 v23, v47, v23, s42
	global_store_dwordx4 v[74:75], v[38:41], off
	ds_read2_b32 v[42:43], v55 offset0:16 offset1:24
	s_nop 0
	v_and_or_b32 v38, v23, s43, v4
	v_bfe_u32 v4, v49, 16, 1
	v_add3_u32 v4, v49, v4, s42
	v_bfe_u32 v23, v51, 16, 1
	v_lshrrev_b32_e32 v4, 16, v4
	v_add3_u32 v23, v51, v23, s42
	v_and_or_b32 v39, v23, s43, v4
	v_bfe_u32 v4, v53, 16, 1
	v_add3_u32 v4, v53, v4, s42
	v_bfe_u32 v23, v69, 16, 1
	v_lshrrev_b32_e32 v4, 16, v4
	v_add3_u32 v23, v69, v23, s42
	v_and_or_b32 v40, v23, s43, v4
	v_bfe_u32 v4, v71, 16, 1
	v_add3_u32 v4, v71, v4, s42
	v_bfe_u32 v23, v73, 16, 1
	v_lshrrev_b32_e32 v4, 16, v4
	v_add3_u32 v23, v73, v23, s42
	v_and_or_b32 v41, v23, s43, v4
	v_or_b32_e32 v4, s22, v56
	v_mul_u32_u24_e32 v4, 0xb00, v4
	v_lshlrev_b32_e32 v4, 1, v4
	v_lshl_add_u64 v[46:47], v[44:45], 0, v[4:5]
	global_store_dwordx4 v[46:47], v[38:41], off
	ds_read2_b32 v[46:47], v55 offset0:49 offset1:57
	ds_read2_b32 v[48:49], v55 offset0:82 offset1:90
	ds_read2_b32 v[50:51], v55 offset0:115 offset1:123
	s_waitcnt lgkmcnt(3)
	v_bfe_u32 v4, v42, 16, 1
	v_add3_u32 v4, v42, v4, s42
	s_waitcnt lgkmcnt(2)
	v_bfe_u32 v23, v46, 16, 1
	ds_read2_b32 v[52:53], v55 offset0:148 offset1:156
	v_lshrrev_b32_e32 v4, 16, v4
	v_add3_u32 v23, v46, v23, s42
	ds_read2_b32 v[68:69], v55 offset0:181 offset1:189
	v_and_or_b32 v38, v23, s43, v4
	s_waitcnt lgkmcnt(3)
	v_bfe_u32 v4, v48, 16, 1
	v_add3_u32 v4, v48, v4, s42
	s_waitcnt lgkmcnt(2)
	v_bfe_u32 v23, v50, 16, 1
	ds_read2_b32 v[70:71], v55 offset0:214 offset1:222
	v_lshrrev_b32_e32 v4, 16, v4
	v_add3_u32 v23, v50, v23, s42
	ds_read2_b32 v[72:73], v55 offset0:247 offset1:255
	v_and_or_b32 v39, v23, s43, v4
	s_waitcnt lgkmcnt(3)
	v_bfe_u32 v4, v52, 16, 1
	v_add3_u32 v4, v52, v4, s42
	s_waitcnt lgkmcnt(2)
	v_bfe_u32 v23, v68, 16, 1
	v_lshrrev_b32_e32 v4, 16, v4
	v_add3_u32 v23, v68, v23, s42
	v_and_or_b32 v40, v23, s43, v4
	s_waitcnt lgkmcnt(1)
	v_bfe_u32 v4, v70, 16, 1
	v_add3_u32 v4, v70, v4, s42
	s_waitcnt lgkmcnt(0)
	v_bfe_u32 v23, v72, 16, 1
	v_lshrrev_b32_e32 v4, 16, v4
	v_add3_u32 v23, v72, v23, s42
	v_and_or_b32 v41, v23, s43, v4
	v_or_b32_e32 v4, s22, v57
	v_mul_u32_u24_e32 v4, 0xb00, v4
	v_lshlrev_b32_e32 v4, 1, v4
	v_lshl_add_u64 v[74:75], v[44:45], 0, v[4:5]
	v_bfe_u32 v4, v43, 16, 1
	v_add3_u32 v4, v43, v4, s42
	v_bfe_u32 v23, v47, 16, 1
	v_lshrrev_b32_e32 v4, 16, v4
	v_add3_u32 v23, v47, v23, s42
	global_store_dwordx4 v[74:75], v[38:41], off
	s_nop 1
	v_and_or_b32 v38, v23, s43, v4
	v_bfe_u32 v4, v49, 16, 1
	v_add3_u32 v4, v49, v4, s42
	v_bfe_u32 v23, v51, 16, 1
	v_lshrrev_b32_e32 v4, 16, v4
	v_add3_u32 v23, v51, v23, s42
	v_and_or_b32 v39, v23, s43, v4
	v_bfe_u32 v4, v53, 16, 1
	v_add3_u32 v4, v53, v4, s42
	v_bfe_u32 v23, v69, 16, 1
	v_lshrrev_b32_e32 v4, 16, v4
	v_add3_u32 v23, v69, v23, s42
	v_and_or_b32 v40, v23, s43, v4
	v_bfe_u32 v4, v71, 16, 1
	v_add3_u32 v4, v71, v4, s42
	v_bfe_u32 v23, v73, 16, 1
	v_lshrrev_b32_e32 v4, 16, v4
	v_add3_u32 v23, v73, v23, s42
	v_and_or_b32 v41, v23, s43, v4
	v_or_b32_e32 v4, s22, v58
	v_mul_u32_u24_e32 v4, 0xb00, v4
	v_lshlrev_b32_e32 v4, 1, v4
	v_lshl_add_u64 v[42:43], v[44:45], 0, v[4:5]
	global_store_dwordx4 v[42:43], v[38:41], off
	s_waitcnt lgkmcnt(0)

.LBB0_54:
	s_andn2_b64 vcc, exec, s[22:23]
	s_cbranch_vccnz .LBB0_58
	s_add_i32 s6, s53, 0xea00
	s_and_b32 s22, s6, 0xffff
	s_mul_i32 s22, s22, 0xba2f
	s_lshr_b32 s23, s22, 16
	s_lshr_b32 s22, s22, 22
	s_mulk_i32 s22, 0x58
	s_sub_i32 s6, s6, s22
	s_and_b32 s54, s23, 0xffc0
	s_and_b32 s55, s6, 0xffff
	v_or_b32_e32 v4, s54, v60
	s_lshl_b32 s6, s55, 7
	v_mul_u32_u24_e32 v4, 0x2c00, v4
	v_lshl_add_u64 v[38:39], s[6:7], 0, v[4:5]
	v_or_b32_e32 v4, s54, v61
	v_mul_u32_u24_e32 v4, 0x2c00, v4
	v_lshl_add_u64 v[40:41], s[6:7], 0, v[4:5]
	v_or_b32_e32 v4, s54, v62
	v_mul_u32_u24_e32 v4, 0x2c00, v4
	v_lshl_add_u64 v[42:43], s[6:7], 0, v[4:5]
	v_or_b32_e32 v4, s54, v63
	v_mul_u32_u24_e32 v4, 0x2c00, v4
	v_lshl_add_u64 v[44:45], s[6:7], 0, v[4:5]
	v_or_b32_e32 v4, s54, v64
	v_mul_u32_u24_e32 v4, 0x2c00, v4
	v_lshl_add_u64 v[46:47], s[6:7], 0, v[4:5]
	v_or_b32_e32 v4, s54, v65
	v_mul_u32_u24_e32 v4, 0x2c00, v4
	v_lshl_add_u64 v[48:49], s[6:7], 0, v[4:5]
	v_or_b32_e32 v4, s54, v66
	v_mul_u32_u24_e32 v4, 0x2c00, v4
	v_lshl_add_u64 v[50:51], s[6:7], 0, v[4:5]
	v_or_b32_e32 v4, s54, v3
	v_mov_b64_e32 v[52:53], s[6:7]
	v_mad_u64_u32 v[52:53], s[22:23], v4, s45, v[52:53]
	s_lshl_b32 s25, s55, 5
	v_lshl_add_u64 v[38:39], v[10:11], 0, v[38:39]
	v_lshl_add_u64 v[40:41], v[10:11], 0, v[40:41]
	v_lshl_add_u64 v[42:43], v[10:11], 0, v[42:43]
	v_lshl_add_u64 v[44:45], v[10:11], 0, v[44:45]
	v_lshl_add_u64 v[46:47], v[10:11], 0, v[46:47]
	v_lshl_add_u64 v[48:49], v[10:11], 0, v[48:49]
	v_lshl_add_u64 v[50:51], v[10:11], 0, v[50:51]
	v_lshl_add_u64 v[52:53], v[10:11], 0, v[52:53]
	s_mov_b64 s[22:23], 0
	v_mov_b32_e32 v4, v59
	v_lshl_add_u64 v[68:69], v[52:53], 0, s[22:23]
	v_lshl_add_u64 v[70:71], v[50:51], 0, s[22:23]
	v_lshl_add_u64 v[72:73], v[48:49], 0, s[22:23]
	v_lshl_add_u64 v[74:75], v[46:47], 0, s[22:23]
	v_lshl_add_u64 v[76:77], v[44:45], 0, s[22:23]
	v_lshl_add_u64 v[78:79], v[42:43], 0, s[22:23]
	v_lshl_add_u64 v[80:81], v[40:41], 0, s[22:23]
	v_lshl_add_u64 v[82:83], v[38:39], 0, s[22:23]
	global_load_dword v100, v[68:69], off nt
	s_nop 0
	global_load_dword v101, v[70:71], off nt
	global_load_dword v102, v[72:73], off nt
	s_nop 0
	global_load_dword v103, v[74:75], off nt
	global_load_dword v104, v[76:77], off nt
	global_load_dword v105, v[78:79], off nt
	global_load_dword v106, v[80:81], off nt
	s_nop 0
	global_load_dword v107, v[82:83], off nt
	s_add_u32 s22, s22, 0x2c000
	s_addc_u32 s23, s23, 0
	v_lshl_add_u64 v[68:69], v[52:53], 0, s[22:23]
	v_lshl_add_u64 v[70:71], v[50:51], 0, s[22:23]
	v_lshl_add_u64 v[72:73], v[48:49], 0, s[22:23]
	v_lshl_add_u64 v[74:75], v[46:47], 0, s[22:23]
	v_lshl_add_u64 v[76:77], v[44:45], 0, s[22:23]
	v_lshl_add_u64 v[78:79], v[42:43], 0, s[22:23]
	v_lshl_add_u64 v[80:81], v[40:41], 0, s[22:23]
	v_lshl_add_u64 v[82:83], v[38:39], 0, s[22:23]
	global_load_dword v108, v[68:69], off nt
	s_nop 0
	global_load_dword v109, v[70:71], off nt
	global_load_dword v110, v[72:73], off nt
	s_nop 0
	global_load_dword v111, v[74:75], off nt
	global_load_dword v112, v[76:77], off nt
	global_load_dword v113, v[78:79], off nt
	global_load_dword v114, v[80:81], off nt
	s_nop 0
	global_load_dword v115, v[82:83], off nt
	s_add_u32 s22, s22, 0x2c000
	s_addc_u32 s23, s23, 0
	v_lshl_add_u64 v[68:69], v[52:53], 0, s[22:23]
	v_lshl_add_u64 v[70:71], v[50:51], 0, s[22:23]
	v_lshl_add_u64 v[72:73], v[48:49], 0, s[22:23]
	v_lshl_add_u64 v[74:75], v[46:47], 0, s[22:23]
	v_lshl_add_u64 v[76:77], v[44:45], 0, s[22:23]
	v_lshl_add_u64 v[78:79], v[42:43], 0, s[22:23]
	v_lshl_add_u64 v[80:81], v[40:41], 0, s[22:23]
	v_lshl_add_u64 v[82:83], v[38:39], 0, s[22:23]
	global_load_dword v116, v[68:69], off nt
	s_nop 0
	global_load_dword v117, v[70:71], off nt
	global_load_dword v118, v[72:73], off nt
	s_nop 0
	global_load_dword v119, v[74:75], off nt
	global_load_dword v120, v[76:77], off nt
	global_load_dword v121, v[78:79], off nt
	global_load_dword v122, v[80:81], off nt
	s_nop 0
	global_load_dword v123, v[82:83], off nt
	s_add_u32 s22, s22, 0x2c000
	s_addc_u32 s23, s23, 0
	v_lshl_add_u64 v[68:69], v[52:53], 0, s[22:23]
	v_lshl_add_u64 v[70:71], v[50:51], 0, s[22:23]
	v_lshl_add_u64 v[72:73], v[48:49], 0, s[22:23]
	v_lshl_add_u64 v[74:75], v[46:47], 0, s[22:23]
	v_lshl_add_u64 v[76:77], v[44:45], 0, s[22:23]
	v_lshl_add_u64 v[78:79], v[42:43], 0, s[22:23]
	v_lshl_add_u64 v[80:81], v[40:41], 0, s[22:23]
	v_lshl_add_u64 v[82:83], v[38:39], 0, s[22:23]
	global_load_dword v124, v[68:69], off nt
	s_nop 0
	global_load_dword v125, v[70:71], off nt
	global_load_dword v126, v[72:73], off nt
	s_nop 0
	global_load_dword v127, v[74:75], off nt
	global_load_dword v128, v[76:77], off nt
	global_load_dword v129, v[78:79], off nt
	global_load_dword v130, v[80:81], off nt
	s_nop 0
	global_load_dword v131, v[82:83], off nt
	s_add_u32 s22, s22, 0x2c000
	s_addc_u32 s23, s23, 0
	v_add_u32_e32 v75, 0x400, v4
	s_waitcnt vmcnt(30)
	ds_write2_b32 v4, v100, v101 offset1:66
	s_waitcnt vmcnt(28)
	ds_write2_b32 v4, v102, v103 offset0:132 offset1:198
	s_waitcnt vmcnt(26)
	ds_write2_b32 v75, v104, v105 offset0:8 offset1:74
	s_waitcnt vmcnt(24)
	ds_write2_b32 v75, v106, v107 offset0:140 offset1:206
	v_add_u32_e32 v4, 0x840, v4
	v_add_u32_e32 v75, 0x400, v4
	s_waitcnt vmcnt(22)
	ds_write2_b32 v4, v108, v109 offset1:66
	s_waitcnt vmcnt(20)
	ds_write2_b32 v4, v110, v111 offset0:132 offset1:198
	s_waitcnt vmcnt(18)
	ds_write2_b32 v75, v112, v113 offset0:8 offset1:74
	s_waitcnt vmcnt(16)
	ds_write2_b32 v75, v114, v115 offset0:140 offset1:206
	v_add_u32_e32 v4, 0x840, v4
	v_add_u32_e32 v75, 0x400, v4
	s_waitcnt vmcnt(14)
	ds_write2_b32 v4, v116, v117 offset1:66
	s_waitcnt vmcnt(12)
	ds_write2_b32 v4, v118, v119 offset0:132 offset1:198
	s_waitcnt vmcnt(10)
	ds_write2_b32 v75, v120, v121 offset0:8 offset1:74
	s_waitcnt vmcnt(8)
	ds_write2_b32 v75, v122, v123 offset0:140 offset1:206
	v_add_u32_e32 v4, 0x840, v4
	v_add_u32_e32 v75, 0x400, v4
	s_waitcnt vmcnt(6)
	ds_write2_b32 v4, v124, v125 offset1:66
	s_waitcnt vmcnt(4)
	ds_write2_b32 v4, v126, v127 offset0:132 offset1:198
	s_waitcnt vmcnt(2)
	ds_write2_b32 v75, v128, v129 offset0:8 offset1:74
	s_waitcnt vmcnt(0)
	ds_write2_b32 v75, v130, v131 offset0:140 offset1:206
	v_add_u32_e32 v4, 0x840, v4
	s_waitcnt lgkmcnt(0)
	ds_read2_b32 v[42:43], v55 offset1:8
	ds_read2_b32 v[46:47], v55 offset0:33 offset1:41
	ds_read2_b32 v[48:49], v55 offset0:66 offset1:74
	ds_read2_b32 v[50:51], v55 offset0:99 offset1:107
	ds_read2_b32 v[52:53], v55 offset0:132 offset1:140
	s_waitcnt lgkmcnt(4)
	v_bfe_u32 v4, v42, 16, 1
	v_add3_u32 v4, v42, v4, s42
	s_waitcnt lgkmcnt(3)
	v_bfe_u32 v23, v46, 16, 1
	v_lshrrev_b32_e32 v4, 16, v4
	v_add3_u32 v23, v46, v23, s42
	ds_read2_b32 v[68:69], v55 offset0:165 offset1:173
	v_and_or_b32 v38, v23, s43, v4
	s_waitcnt lgkmcnt(3)
	v_bfe_u32 v4, v48, 16, 1
	v_add3_u32 v4, v48, v4, s42
	s_waitcnt lgkmcnt(2)
	v_bfe_u32 v23, v50, 16, 1
	ds_read2_b32 v[70:71], v55 offset0:198 offset1:206
	v_lshrrev_b32_e32 v4, 16, v4
	v_add3_u32 v23, v50, v23, s42
	ds_read2_b32 v[72:73], v55 offset0:231 offset1:239
	v_and_or_b32 v39, v23, s43, v4
	s_waitcnt lgkmcnt(3)
	v_bfe_u32 v4, v52, 16, 1
	s_lshl_b32 s6, s55, 6
	v_add3_u32 v4, v52, v4, s42
	s_waitcnt lgkmcnt(2)
	v_bfe_u32 v23, v68, 16, 1
	s_and_b32 s6, s6, 0x1f00
	v_lshrrev_b32_e32 v4, 16, v4
	v_add3_u32 v23, v68, v23, s42
	s_or_b32 s22, s6, 0x80
	s_and_b32 s6, 0xffff, s54
	v_and_or_b32 v40, v23, s43, v4
	s_waitcnt lgkmcnt(1)
	v_bfe_u32 v4, v70, 16, 1
	s_lshl_b32 s6, s6, 1
	v_add3_u32 v4, v70, v4, s42
	s_waitcnt lgkmcnt(0)
	v_bfe_u32 v23, v72, 16, 1
	v_lshl_add_u64 v[44:45], v[32:33], 0, s[6:7]
	v_lshrrev_b32_e32 v4, 16, v4
	v_add3_u32 v23, v72, v23, s42
	s_and_b32 s6, s25, 0x60
	v_and_or_b32 v41, v23, s43, v4
	v_or_b32_e32 v4, s6, v54
	v_or_b32_e32 v4, s22, v4
	v_lshlrev_b32_e32 v4, 11, v4
	v_lshl_add_u64 v[74:75], v[44:45], 0, v[4:5]
	v_bfe_u32 v4, v43, 16, 1
	v_add3_u32 v4, v43, v4, s42
	v_bfe_u32 v23, v47, 16, 1
	v_lshrrev_b32_e32 v4, 16, v4
	v_add3_u32 v23, v47, v23, s42
	global_store_dwordx4 v[74:75], v[38:41], off
	ds_read2_b32 v[42:43], v55 offset0:16 offset1:24
	s_nop 0
	v_and_or_b32 v38, v23, s43, v4
	v_bfe_u32 v4, v49, 16, 1
	v_add3_u32 v4, v49, v4, s42
	v_bfe_u32 v23, v51, 16, 1
	v_lshrrev_b32_e32 v4, 16, v4
	v_add3_u32 v23, v51, v23, s42
	v_and_or_b32 v39, v23, s43, v4
	v_bfe_u32 v4, v53, 16, 1
	v_add3_u32 v4, v53, v4, s42
	v_bfe_u32 v23, v69, 16, 1
	v_lshrrev_b32_e32 v4, 16, v4
	v_add3_u32 v23, v69, v23, s42
	v_and_or_b32 v40, v23, s43, v4
	v_bfe_u32 v4, v71, 16, 1
	v_add3_u32 v4, v71, v4, s42
	v_bfe_u32 v23, v73, 16, 1
	v_lshrrev_b32_e32 v4, 16, v4
	v_add3_u32 v23, v73, v23, s42
	v_and_or_b32 v41, v23, s43, v4
	v_or_b32_e32 v4, s6, v56
	v_or_b32_e32 v4, s22, v4
	v_lshlrev_b32_e32 v4, 11, v4
	v_lshl_add_u64 v[46:47], v[44:45], 0, v[4:5]
	global_store_dwordx4 v[46:47], v[38:41], off
	ds_read2_b32 v[46:47], v55 offset0:49 offset1:57
	ds_read2_b32 v[48:49], v55 offset0:82 offset1:90
	ds_read2_b32 v[50:51], v55 offset0:115 offset1:123
	s_waitcnt lgkmcnt(3)
	v_bfe_u32 v4, v42, 16, 1
	v_add3_u32 v4, v42, v4, s42
	s_waitcnt lgkmcnt(2)
	v_bfe_u32 v23, v46, 16, 1
	ds_read2_b32 v[52:53], v55 offset0:148 offset1:156
	v_lshrrev_b32_e32 v4, 16, v4
	v_add3_u32 v23, v46, v23, s42
	ds_read2_b32 v[68:69], v55 offset0:181 offset1:189
	v_and_or_b32 v38, v23, s43, v4
	s_waitcnt lgkmcnt(3)
	v_bfe_u32 v4, v48, 16, 1
	v_add3_u32 v4, v48, v4, s42
	s_waitcnt lgkmcnt(2)
	v_bfe_u32 v23, v50, 16, 1
	ds_read2_b32 v[70:71], v55 offset0:214 offset1:222
	v_lshrrev_b32_e32 v4, 16, v4
	v_add3_u32 v23, v50, v23, s42
	ds_read2_b32 v[72:73], v55 offset0:247 offset1:255
	v_and_or_b32 v39, v23, s43, v4
	s_waitcnt lgkmcnt(3)
	v_bfe_u32 v4, v52, 16, 1
	v_add3_u32 v4, v52, v4, s42
	s_waitcnt lgkmcnt(2)
	v_bfe_u32 v23, v68, 16, 1
	v_lshrrev_b32_e32 v4, 16, v4
	v_add3_u32 v23, v68, v23, s42
	v_and_or_b32 v40, v23, s43, v4
	s_waitcnt lgkmcnt(1)
	v_bfe_u32 v4, v70, 16, 1
	v_add3_u32 v4, v70, v4, s42
	s_waitcnt lgkmcnt(0)
	v_bfe_u32 v23, v72, 16, 1
	v_lshrrev_b32_e32 v4, 16, v4
	v_add3_u32 v23, v72, v23, s42
	v_and_or_b32 v41, v23, s43, v4
	v_or_b32_e32 v4, s6, v57
	v_or_b32_e32 v4, s22, v4
	v_lshlrev_b32_e32 v4, 11, v4
	v_lshl_add_u64 v[74:75], v[44:45], 0, v[4:5]
	v_bfe_u32 v4, v43, 16, 1
	v_add3_u32 v4, v43, v4, s42
	v_bfe_u32 v23, v47, 16, 1
	v_lshrrev_b32_e32 v4, 16, v4
	v_add3_u32 v23, v47, v23, s42
	global_store_dwordx4 v[74:75], v[38:41], off
	s_nop 1
	v_and_or_b32 v38, v23, s43, v4
	v_bfe_u32 v4, v49, 16, 1
	v_add3_u32 v4, v49, v4, s42
	v_bfe_u32 v23, v51, 16, 1
	v_lshrrev_b32_e32 v4, 16, v4
	v_add3_u32 v23, v51, v23, s42
	v_and_or_b32 v39, v23, s43, v4
	v_bfe_u32 v4, v53, 16, 1
	v_add3_u32 v4, v53, v4, s42
	v_bfe_u32 v23, v69, 16, 1
	v_lshrrev_b32_e32 v4, 16, v4
	v_add3_u32 v23, v69, v23, s42
	v_and_or_b32 v40, v23, s43, v4
	v_bfe_u32 v4, v71, 16, 1
	v_add3_u32 v4, v71, v4, s42
	v_bfe_u32 v23, v73, 16, 1
	v_lshrrev_b32_e32 v4, 16, v4
	v_add3_u32 v23, v73, v23, s42
	v_and_or_b32 v41, v23, s43, v4
	v_or_b32_e32 v4, s6, v58
	v_or_b32_e32 v4, s22, v4
	v_lshlrev_b32_e32 v4, 11, v4
	v_lshl_add_u64 v[42:43], v[44:45], 0, v[4:5]
	global_store_dwordx4 v[42:43], v[38:41], off
	s_waitcnt lgkmcnt(0)

.LBB0_59:
	s_andn2_b64 vcc, exec, s[22:23]
	s_cbranch_vccnz .LBB0_63
	s_add_i32 s6, s53, 0xef80
	s_and_b32 s22, s6, 0xffff
	s_mul_i32 s22, s22, 0xba2f
	s_lshr_b32 s23, s22, 16
	s_lshr_b32 s22, s22, 22
	s_mulk_i32 s22, 0x58
	s_sub_i32 s6, s6, s22
	s_and_b32 s54, s23, 0xffc0
	s_and_b32 s55, s6, 0xffff
	v_or_b32_e32 v4, s54, v60
	s_lshl_b32 s6, s55, 7
	v_mul_u32_u24_e32 v4, 0x2c00, v4
	v_lshl_add_u64 v[38:39], s[6:7], 0, v[4:5]
	v_or_b32_e32 v4, s54, v61
	v_mul_u32_u24_e32 v4, 0x2c00, v4
	v_lshl_add_u64 v[40:41], s[6:7], 0, v[4:5]
	v_or_b32_e32 v4, s54, v62
	v_mul_u32_u24_e32 v4, 0x2c00, v4
	v_lshl_add_u64 v[42:43], s[6:7], 0, v[4:5]
	v_or_b32_e32 v4, s54, v63
	v_mul_u32_u24_e32 v4, 0x2c00, v4
	v_lshl_add_u64 v[44:45], s[6:7], 0, v[4:5]
	v_or_b32_e32 v4, s54, v64
	v_mul_u32_u24_e32 v4, 0x2c00, v4
	v_lshl_add_u64 v[46:47], s[6:7], 0, v[4:5]
	v_or_b32_e32 v4, s54, v65
	v_mul_u32_u24_e32 v4, 0x2c00, v4
	v_lshl_add_u64 v[48:49], s[6:7], 0, v[4:5]
	v_or_b32_e32 v4, s54, v66
	v_mul_u32_u24_e32 v4, 0x2c00, v4
	v_lshl_add_u64 v[50:51], s[6:7], 0, v[4:5]
	v_or_b32_e32 v4, s54, v3
	v_mov_b64_e32 v[52:53], s[6:7]
	v_mad_u64_u32 v[52:53], s[22:23], v4, s45, v[52:53]
	s_lshl_b32 s25, s55, 5
	v_lshl_add_u64 v[38:39], v[12:13], 0, v[38:39]
	v_lshl_add_u64 v[40:41], v[12:13], 0, v[40:41]
	v_lshl_add_u64 v[42:43], v[12:13], 0, v[42:43]
	v_lshl_add_u64 v[44:45], v[12:13], 0, v[44:45]
	v_lshl_add_u64 v[46:47], v[12:13], 0, v[46:47]
	v_lshl_add_u64 v[48:49], v[12:13], 0, v[48:49]
	v_lshl_add_u64 v[50:51], v[12:13], 0, v[50:51]
	v_lshl_add_u64 v[52:53], v[12:13], 0, v[52:53]
	s_mov_b64 s[22:23], 0
	v_mov_b32_e32 v4, v59
	v_lshl_add_u64 v[68:69], v[52:53], 0, s[22:23]
	v_lshl_add_u64 v[70:71], v[50:51], 0, s[22:23]
	v_lshl_add_u64 v[72:73], v[48:49], 0, s[22:23]
	v_lshl_add_u64 v[74:75], v[46:47], 0, s[22:23]
	v_lshl_add_u64 v[76:77], v[44:45], 0, s[22:23]
	v_lshl_add_u64 v[78:79], v[42:43], 0, s[22:23]
	v_lshl_add_u64 v[80:81], v[40:41], 0, s[22:23]
	v_lshl_add_u64 v[82:83], v[38:39], 0, s[22:23]
	global_load_dword v100, v[68:69], off nt
	s_nop 0
	global_load_dword v101, v[70:71], off nt
	global_load_dword v102, v[72:73], off nt
	s_nop 0
	global_load_dword v103, v[74:75], off nt
	global_load_dword v104, v[76:77], off nt
	global_load_dword v105, v[78:79], off nt
	global_load_dword v106, v[80:81], off nt
	s_nop 0
	global_load_dword v107, v[82:83], off nt
	s_add_u32 s22, s22, 0x2c000
	s_addc_u32 s23, s23, 0
	v_lshl_add_u64 v[68:69], v[52:53], 0, s[22:23]
	v_lshl_add_u64 v[70:71], v[50:51], 0, s[22:23]
	v_lshl_add_u64 v[72:73], v[48:49], 0, s[22:23]
	v_lshl_add_u64 v[74:75], v[46:47], 0, s[22:23]
	v_lshl_add_u64 v[76:77], v[44:45], 0, s[22:23]
	v_lshl_add_u64 v[78:79], v[42:43], 0, s[22:23]
	v_lshl_add_u64 v[80:81], v[40:41], 0, s[22:23]
	v_lshl_add_u64 v[82:83], v[38:39], 0, s[22:23]
	global_load_dword v108, v[68:69], off nt
	s_nop 0
	global_load_dword v109, v[70:71], off nt
	global_load_dword v110, v[72:73], off nt
	s_nop 0
	global_load_dword v111, v[74:75], off nt
	global_load_dword v112, v[76:77], off nt
	global_load_dword v113, v[78:79], off nt
	global_load_dword v114, v[80:81], off nt
	s_nop 0
	global_load_dword v115, v[82:83], off nt
	s_add_u32 s22, s22, 0x2c000
	s_addc_u32 s23, s23, 0
	v_lshl_add_u64 v[68:69], v[52:53], 0, s[22:23]
	v_lshl_add_u64 v[70:71], v[50:51], 0, s[22:23]
	v_lshl_add_u64 v[72:73], v[48:49], 0, s[22:23]
	v_lshl_add_u64 v[74:75], v[46:47], 0, s[22:23]
	v_lshl_add_u64 v[76:77], v[44:45], 0, s[22:23]
	v_lshl_add_u64 v[78:79], v[42:43], 0, s[22:23]
	v_lshl_add_u64 v[80:81], v[40:41], 0, s[22:23]
	v_lshl_add_u64 v[82:83], v[38:39], 0, s[22:23]
	global_load_dword v116, v[68:69], off nt
	s_nop 0
	global_load_dword v117, v[70:71], off nt
	global_load_dword v118, v[72:73], off nt
	s_nop 0
	global_load_dword v119, v[74:75], off nt
	global_load_dword v120, v[76:77], off nt
	global_load_dword v121, v[78:79], off nt
	global_load_dword v122, v[80:81], off nt
	s_nop 0
	global_load_dword v123, v[82:83], off nt
	s_add_u32 s22, s22, 0x2c000
	s_addc_u32 s23, s23, 0
	v_lshl_add_u64 v[68:69], v[52:53], 0, s[22:23]
	v_lshl_add_u64 v[70:71], v[50:51], 0, s[22:23]
	v_lshl_add_u64 v[72:73], v[48:49], 0, s[22:23]
	v_lshl_add_u64 v[74:75], v[46:47], 0, s[22:23]
	v_lshl_add_u64 v[76:77], v[44:45], 0, s[22:23]
	v_lshl_add_u64 v[78:79], v[42:43], 0, s[22:23]
	v_lshl_add_u64 v[80:81], v[40:41], 0, s[22:23]
	v_lshl_add_u64 v[82:83], v[38:39], 0, s[22:23]
	global_load_dword v124, v[68:69], off nt
	s_nop 0
	global_load_dword v125, v[70:71], off nt
	global_load_dword v126, v[72:73], off nt
	s_nop 0
	global_load_dword v127, v[74:75], off nt
	global_load_dword v128, v[76:77], off nt
	global_load_dword v129, v[78:79], off nt
	global_load_dword v130, v[80:81], off nt
	s_nop 0
	global_load_dword v131, v[82:83], off nt
	s_add_u32 s22, s22, 0x2c000
	s_addc_u32 s23, s23, 0
	v_add_u32_e32 v75, 0x400, v4
	s_waitcnt vmcnt(30)
	ds_write2_b32 v4, v100, v101 offset1:66
	s_waitcnt vmcnt(28)
	ds_write2_b32 v4, v102, v103 offset0:132 offset1:198
	s_waitcnt vmcnt(26)
	ds_write2_b32 v75, v104, v105 offset0:8 offset1:74
	s_waitcnt vmcnt(24)
	ds_write2_b32 v75, v106, v107 offset0:140 offset1:206
	v_add_u32_e32 v4, 0x840, v4
	v_add_u32_e32 v75, 0x400, v4
	s_waitcnt vmcnt(22)
	ds_write2_b32 v4, v108, v109 offset1:66
	s_waitcnt vmcnt(20)
	ds_write2_b32 v4, v110, v111 offset0:132 offset1:198
	s_waitcnt vmcnt(18)
	ds_write2_b32 v75, v112, v113 offset0:8 offset1:74
	s_waitcnt vmcnt(16)
	ds_write2_b32 v75, v114, v115 offset0:140 offset1:206
	v_add_u32_e32 v4, 0x840, v4
	v_add_u32_e32 v75, 0x400, v4
	s_waitcnt vmcnt(14)
	ds_write2_b32 v4, v116, v117 offset1:66
	s_waitcnt vmcnt(12)
	ds_write2_b32 v4, v118, v119 offset0:132 offset1:198
	s_waitcnt vmcnt(10)
	ds_write2_b32 v75, v120, v121 offset0:8 offset1:74
	s_waitcnt vmcnt(8)
	ds_write2_b32 v75, v122, v123 offset0:140 offset1:206
	v_add_u32_e32 v4, 0x840, v4
	v_add_u32_e32 v75, 0x400, v4
	s_waitcnt vmcnt(6)
	ds_write2_b32 v4, v124, v125 offset1:66
	s_waitcnt vmcnt(4)
	ds_write2_b32 v4, v126, v127 offset0:132 offset1:198
	s_waitcnt vmcnt(2)
	ds_write2_b32 v75, v128, v129 offset0:8 offset1:74
	s_waitcnt vmcnt(0)
	ds_write2_b32 v75, v130, v131 offset0:140 offset1:206
	v_add_u32_e32 v4, 0x840, v4
	s_waitcnt lgkmcnt(0)
	ds_read2_b32 v[42:43], v55 offset1:8
	ds_read2_b32 v[46:47], v55 offset0:33 offset1:41
	ds_read2_b32 v[48:49], v55 offset0:66 offset1:74
	ds_read2_b32 v[50:51], v55 offset0:99 offset1:107
	ds_read2_b32 v[52:53], v55 offset0:132 offset1:140
	s_waitcnt lgkmcnt(4)
	v_bfe_u32 v4, v42, 16, 1
	v_add3_u32 v4, v42, v4, s42
	s_waitcnt lgkmcnt(3)
	v_bfe_u32 v23, v46, 16, 1
	v_lshrrev_b32_e32 v4, 16, v4
	v_add3_u32 v23, v46, v23, s42
	ds_read2_b32 v[68:69], v55 offset0:165 offset1:173
	v_and_or_b32 v38, v23, s43, v4
	s_waitcnt lgkmcnt(3)
	v_bfe_u32 v4, v48, 16, 1
	v_add3_u32 v4, v48, v4, s42
	s_waitcnt lgkmcnt(2)
	v_bfe_u32 v23, v50, 16, 1
	ds_read2_b32 v[70:71], v55 offset0:198 offset1:206
	v_lshrrev_b32_e32 v4, 16, v4
	v_add3_u32 v23, v50, v23, s42
	ds_read2_b32 v[72:73], v55 offset0:231 offset1:239
	v_and_or_b32 v39, v23, s43, v4
	s_waitcnt lgkmcnt(3)
	v_bfe_u32 v4, v52, 16, 1
	v_add3_u32 v4, v52, v4, s42
	s_waitcnt lgkmcnt(2)
	v_bfe_u32 v23, v68, 16, 1
	s_lshl_b32 s6, s55, 6
	v_lshrrev_b32_e32 v4, 16, v4
	v_add3_u32 v23, v68, v23, s42
	s_and_b32 s22, s6, 0x1f00
	s_and_b32 s6, 0xffff, s54
	v_and_or_b32 v40, v23, s43, v4
	s_waitcnt lgkmcnt(1)
	v_bfe_u32 v4, v70, 16, 1
	s_lshl_b32 s6, s6, 1
	v_add3_u32 v4, v70, v4, s42
	s_waitcnt lgkmcnt(0)
	v_bfe_u32 v23, v72, 16, 1
	v_lshl_add_u64 v[44:45], v[32:33], 0, s[6:7]
	v_lshrrev_b32_e32 v4, 16, v4
	v_add3_u32 v23, v72, v23, s42
	s_and_b32 s6, s25, 0x60
	v_and_or_b32 v41, v23, s43, v4
	v_or_b32_e32 v4, s6, v54
	v_or_b32_e32 v4, s22, v4
	v_lshlrev_b32_e32 v4, 11, v4
	v_lshl_add_u64 v[74:75], v[44:45], 0, v[4:5]
	v_bfe_u32 v4, v43, 16, 1
	v_add3_u32 v4, v43, v4, s42
	v_bfe_u32 v23, v47, 16, 1
	v_lshrrev_b32_e32 v4, 16, v4
	v_add3_u32 v23, v47, v23, s42
	global_store_dwordx4 v[74:75], v[38:41], off
	ds_read2_b32 v[42:43], v55 offset0:16 offset1:24
	s_nop 0
	v_and_or_b32 v38, v23, s43, v4
	v_bfe_u32 v4, v49, 16, 1
	v_add3_u32 v4, v49, v4, s42
	v_bfe_u32 v23, v51, 16, 1
	v_lshrrev_b32_e32 v4, 16, v4
	v_add3_u32 v23, v51, v23, s42
	v_and_or_b32 v39, v23, s43, v4
	v_bfe_u32 v4, v53, 16, 1
	v_add3_u32 v4, v53, v4, s42
	v_bfe_u32 v23, v69, 16, 1
	v_lshrrev_b32_e32 v4, 16, v4
	v_add3_u32 v23, v69, v23, s42
	v_and_or_b32 v40, v23, s43, v4
	v_bfe_u32 v4, v71, 16, 1
	v_add3_u32 v4, v71, v4, s42
	v_bfe_u32 v23, v73, 16, 1
	v_lshrrev_b32_e32 v4, 16, v4
	v_add3_u32 v23, v73, v23, s42
	v_and_or_b32 v41, v23, s43, v4
	v_or_b32_e32 v4, s6, v56
	v_or_b32_e32 v4, s22, v4
	v_lshlrev_b32_e32 v4, 11, v4
	v_lshl_add_u64 v[46:47], v[44:45], 0, v[4:5]
	global_store_dwordx4 v[46:47], v[38:41], off
	ds_read2_b32 v[46:47], v55 offset0:49 offset1:57
	ds_read2_b32 v[48:49], v55 offset0:82 offset1:90
	ds_read2_b32 v[50:51], v55 offset0:115 offset1:123
	s_waitcnt lgkmcnt(3)
	v_bfe_u32 v4, v42, 16, 1
	v_add3_u32 v4, v42, v4, s42
	s_waitcnt lgkmcnt(2)
	v_bfe_u32 v23, v46, 16, 1
	ds_read2_b32 v[52:53], v55 offset0:148 offset1:156
	v_lshrrev_b32_e32 v4, 16, v4
	v_add3_u32 v23, v46, v23, s42
	ds_read2_b32 v[68:69], v55 offset0:181 offset1:189
	v_and_or_b32 v38, v23, s43, v4
	s_waitcnt lgkmcnt(3)
	v_bfe_u32 v4, v48, 16, 1
	v_add3_u32 v4, v48, v4, s42
	s_waitcnt lgkmcnt(2)
	v_bfe_u32 v23, v50, 16, 1
	ds_read2_b32 v[70:71], v55 offset0:214 offset1:222
	v_lshrrev_b32_e32 v4, 16, v4
	v_add3_u32 v23, v50, v23, s42
	ds_read2_b32 v[72:73], v55 offset0:247 offset1:255
	v_and_or_b32 v39, v23, s43, v4
	s_waitcnt lgkmcnt(3)
	v_bfe_u32 v4, v52, 16, 1
	v_add3_u32 v4, v52, v4, s42
	s_waitcnt lgkmcnt(2)
	v_bfe_u32 v23, v68, 16, 1
	v_lshrrev_b32_e32 v4, 16, v4
	v_add3_u32 v23, v68, v23, s42
	v_and_or_b32 v40, v23, s43, v4
	s_waitcnt lgkmcnt(1)
	v_bfe_u32 v4, v70, 16, 1
	v_add3_u32 v4, v70, v4, s42
	s_waitcnt lgkmcnt(0)
	v_bfe_u32 v23, v72, 16, 1
	v_lshrrev_b32_e32 v4, 16, v4
	v_add3_u32 v23, v72, v23, s42
	v_and_or_b32 v41, v23, s43, v4
	v_or_b32_e32 v4, s6, v57
	v_or_b32_e32 v4, s22, v4
	v_lshlrev_b32_e32 v4, 11, v4
	v_lshl_add_u64 v[74:75], v[44:45], 0, v[4:5]
	v_bfe_u32 v4, v43, 16, 1
	v_add3_u32 v4, v43, v4, s42
	v_bfe_u32 v23, v47, 16, 1
	v_lshrrev_b32_e32 v4, 16, v4
	v_add3_u32 v23, v47, v23, s42
	global_store_dwordx4 v[74:75], v[38:41], off
	s_nop 1
	v_and_or_b32 v38, v23, s43, v4
	v_bfe_u32 v4, v49, 16, 1
	v_add3_u32 v4, v49, v4, s42
	v_bfe_u32 v23, v51, 16, 1
	v_lshrrev_b32_e32 v4, 16, v4
	v_add3_u32 v23, v51, v23, s42
	v_and_or_b32 v39, v23, s43, v4
	v_bfe_u32 v4, v53, 16, 1
	v_add3_u32 v4, v53, v4, s42
	v_bfe_u32 v23, v69, 16, 1
	v_lshrrev_b32_e32 v4, 16, v4
	v_add3_u32 v23, v69, v23, s42
	v_and_or_b32 v40, v23, s43, v4
	v_bfe_u32 v4, v71, 16, 1
	v_add3_u32 v4, v71, v4, s42
	v_bfe_u32 v23, v73, 16, 1
	v_lshrrev_b32_e32 v4, 16, v4
	v_add3_u32 v23, v73, v23, s42
	v_and_or_b32 v41, v23, s43, v4
	v_or_b32_e32 v4, s6, v58
	v_or_b32_e32 v4, s22, v4
	v_lshlrev_b32_e32 v4, 11, v4
	v_lshl_add_u64 v[42:43], v[44:45], 0, v[4:5]
	global_store_dwordx4 v[42:43], v[38:41], off
	s_waitcnt lgkmcnt(0)

.LBB0_64:
	s_andn2_b64 vcc, exec, s[22:23]
	s_cbranch_vccnz .LBB0_68
	s_and_b32 s6, s47, 0x1ffc0
	v_or_b32_e32 v4, s6, v60
	v_lshl_or_b32 v4, v4, 12, s24
	v_lshl_add_u64 v[38:39], v[14:15], 0, v[4:5]
	v_or_b32_e32 v4, s6, v61
	v_lshl_or_b32 v4, v4, 12, s24
	v_lshl_add_u64 v[40:41], v[14:15], 0, v[4:5]
	v_or_b32_e32 v4, s6, v62
	v_lshl_or_b32 v4, v4, 12, s24
	v_lshl_add_u64 v[42:43], v[14:15], 0, v[4:5]
	v_or_b32_e32 v4, s6, v63
	v_lshl_or_b32 v4, v4, 12, s24
	v_lshl_add_u64 v[44:45], v[14:15], 0, v[4:5]
	v_or_b32_e32 v4, s6, v64
	v_lshl_or_b32 v4, v4, 12, s24
	v_lshl_add_u64 v[46:47], v[14:15], 0, v[4:5]
	v_or_b32_e32 v4, s6, v65
	v_lshl_or_b32 v4, v4, 12, s24
	v_lshl_add_u64 v[48:49], v[14:15], 0, v[4:5]
	v_or_b32_e32 v4, s6, v66
	v_lshl_or_b32 v4, v4, 12, s24
	v_lshl_add_u64 v[50:51], v[14:15], 0, v[4:5]
	v_or_b32_e32 v4, s6, v3
	v_lshl_or_b32 v4, v4, 12, s24
	v_lshl_add_u64 v[52:53], v[14:15], 0, v[4:5]
	s_mov_b64 s[22:23], 0
	v_mov_b32_e32 v4, v59
	v_lshl_add_u64 v[68:69], v[52:53], 0, s[22:23]
	v_lshl_add_u64 v[70:71], v[50:51], 0, s[22:23]
	v_lshl_add_u64 v[72:73], v[48:49], 0, s[22:23]
	v_lshl_add_u64 v[74:75], v[46:47], 0, s[22:23]
	v_lshl_add_u64 v[76:77], v[44:45], 0, s[22:23]
	v_lshl_add_u64 v[78:79], v[42:43], 0, s[22:23]
	v_lshl_add_u64 v[80:81], v[40:41], 0, s[22:23]
	v_lshl_add_u64 v[82:83], v[38:39], 0, s[22:23]
	global_load_dword v100, v[68:69], off nt
	s_nop 0
	global_load_dword v101, v[70:71], off nt
	global_load_dword v102, v[72:73], off nt
	s_nop 0
	global_load_dword v103, v[74:75], off nt
	global_load_dword v104, v[76:77], off nt
	global_load_dword v105, v[78:79], off nt
	global_load_dword v106, v[80:81], off nt
	s_nop 0
	global_load_dword v107, v[82:83], off nt
	s_add_u32 s22, s22, 0x10000
	s_addc_u32 s23, s23, 0
	v_lshl_add_u64 v[68:69], v[52:53], 0, s[22:23]
	v_lshl_add_u64 v[70:71], v[50:51], 0, s[22:23]
	v_lshl_add_u64 v[72:73], v[48:49], 0, s[22:23]
	v_lshl_add_u64 v[74:75], v[46:47], 0, s[22:23]
	v_lshl_add_u64 v[76:77], v[44:45], 0, s[22:23]
	v_lshl_add_u64 v[78:79], v[42:43], 0, s[22:23]
	v_lshl_add_u64 v[80:81], v[40:41], 0, s[22:23]
	v_lshl_add_u64 v[82:83], v[38:39], 0, s[22:23]
	global_load_dword v108, v[68:69], off nt
	s_nop 0
	global_load_dword v109, v[70:71], off nt
	global_load_dword v110, v[72:73], off nt
	s_nop 0
	global_load_dword v111, v[74:75], off nt
	global_load_dword v112, v[76:77], off nt
	global_load_dword v113, v[78:79], off nt
	global_load_dword v114, v[80:81], off nt
	s_nop 0
	global_load_dword v115, v[82:83], off nt
	s_add_u32 s22, s22, 0x10000
	s_addc_u32 s23, s23, 0
	v_lshl_add_u64 v[68:69], v[52:53], 0, s[22:23]
	v_lshl_add_u64 v[70:71], v[50:51], 0, s[22:23]
	v_lshl_add_u64 v[72:73], v[48:49], 0, s[22:23]
	v_lshl_add_u64 v[74:75], v[46:47], 0, s[22:23]
	v_lshl_add_u64 v[76:77], v[44:45], 0, s[22:23]
	v_lshl_add_u64 v[78:79], v[42:43], 0, s[22:23]
	v_lshl_add_u64 v[80:81], v[40:41], 0, s[22:23]
	v_lshl_add_u64 v[82:83], v[38:39], 0, s[22:23]
	global_load_dword v116, v[68:69], off nt
	s_nop 0
	global_load_dword v117, v[70:71], off nt
	global_load_dword v118, v[72:73], off nt
	s_nop 0
	global_load_dword v119, v[74:75], off nt
	global_load_dword v120, v[76:77], off nt
	global_load_dword v121, v[78:79], off nt
	global_load_dword v122, v[80:81], off nt
	s_nop 0
	global_load_dword v123, v[82:83], off nt
	s_add_u32 s22, s22, 0x10000
	s_addc_u32 s23, s23, 0
	v_lshl_add_u64 v[68:69], v[52:53], 0, s[22:23]
	v_lshl_add_u64 v[70:71], v[50:51], 0, s[22:23]
	v_lshl_add_u64 v[72:73], v[48:49], 0, s[22:23]
	v_lshl_add_u64 v[74:75], v[46:47], 0, s[22:23]
	v_lshl_add_u64 v[76:77], v[44:45], 0, s[22:23]
	v_lshl_add_u64 v[78:79], v[42:43], 0, s[22:23]
	v_lshl_add_u64 v[80:81], v[40:41], 0, s[22:23]
	v_lshl_add_u64 v[82:83], v[38:39], 0, s[22:23]
	global_load_dword v124, v[68:69], off nt
	s_nop 0
	global_load_dword v125, v[70:71], off nt
	global_load_dword v126, v[72:73], off nt
	s_nop 0
	global_load_dword v127, v[74:75], off nt
	global_load_dword v128, v[76:77], off nt
	global_load_dword v129, v[78:79], off nt
	global_load_dword v130, v[80:81], off nt
	s_nop 0
	global_load_dword v131, v[82:83], off nt
	s_add_u32 s22, s22, 0x10000
	s_addc_u32 s23, s23, 0
	v_add_u32_e32 v75, 0x400, v4
	s_waitcnt vmcnt(30)
	ds_write2_b32 v4, v100, v101 offset1:66
	s_waitcnt vmcnt(28)
	ds_write2_b32 v4, v102, v103 offset0:132 offset1:198
	s_waitcnt vmcnt(26)
	ds_write2_b32 v75, v104, v105 offset0:8 offset1:74
	s_waitcnt vmcnt(24)
	ds_write2_b32 v75, v106, v107 offset0:140 offset1:206
	v_add_u32_e32 v4, 0x840, v4
	v_add_u32_e32 v75, 0x400, v4
	s_waitcnt vmcnt(22)
	ds_write2_b32 v4, v108, v109 offset1:66
	s_waitcnt vmcnt(20)
	ds_write2_b32 v4, v110, v111 offset0:132 offset1:198
	s_waitcnt vmcnt(18)
	ds_write2_b32 v75, v112, v113 offset0:8 offset1:74
	s_waitcnt vmcnt(16)
	ds_write2_b32 v75, v114, v115 offset0:140 offset1:206
	v_add_u32_e32 v4, 0x840, v4
	v_add_u32_e32 v75, 0x400, v4
	s_waitcnt vmcnt(14)
	ds_write2_b32 v4, v116, v117 offset1:66
	s_waitcnt vmcnt(12)
	ds_write2_b32 v4, v118, v119 offset0:132 offset1:198
	s_waitcnt vmcnt(10)
	ds_write2_b32 v75, v120, v121 offset0:8 offset1:74
	s_waitcnt vmcnt(8)
	ds_write2_b32 v75, v122, v123 offset0:140 offset1:206
	v_add_u32_e32 v4, 0x840, v4
	v_add_u32_e32 v75, 0x400, v4
	s_waitcnt vmcnt(6)
	ds_write2_b32 v4, v124, v125 offset1:66
	s_waitcnt vmcnt(4)
	ds_write2_b32 v4, v126, v127 offset0:132 offset1:198
	s_waitcnt vmcnt(2)
	ds_write2_b32 v75, v128, v129 offset0:8 offset1:74
	s_waitcnt vmcnt(0)
	ds_write2_b32 v75, v130, v131 offset0:140 offset1:206
	v_add_u32_e32 v4, 0x840, v4
	s_waitcnt lgkmcnt(0)
	ds_read2_b32 v[42:43], v55 offset1:8
	ds_read2_b32 v[46:47], v55 offset0:33 offset1:41
	ds_read2_b32 v[48:49], v55 offset0:66 offset1:74
	ds_read2_b32 v[50:51], v55 offset0:99 offset1:107
	ds_read2_b32 v[52:53], v55 offset0:132 offset1:140
	s_waitcnt lgkmcnt(4)
	v_bfe_u32 v4, v42, 16, 1
	v_add3_u32 v4, v42, v4, s42
	s_waitcnt lgkmcnt(3)
	v_bfe_u32 v23, v46, 16, 1
	v_lshrrev_b32_e32 v4, 16, v4
	v_add3_u32 v23, v46, v23, s42
	ds_read2_b32 v[68:69], v55 offset0:165 offset1:173
	v_and_or_b32 v38, v23, s43, v4
	s_waitcnt lgkmcnt(3)
	v_bfe_u32 v4, v48, 16, 1
	v_add3_u32 v4, v48, v4, s42
	s_waitcnt lgkmcnt(2)
	v_bfe_u32 v23, v50, 16, 1
	ds_read2_b32 v[70:71], v55 offset0:198 offset1:206
	v_lshrrev_b32_e32 v4, 16, v4
	v_add3_u32 v23, v50, v23, s42
	ds_read2_b32 v[72:73], v55 offset0:231 offset1:239
	v_and_or_b32 v39, v23, s43, v4
	s_waitcnt lgkmcnt(3)
	v_bfe_u32 v4, v52, 16, 1
	v_add3_u32 v4, v52, v4, s42
	s_waitcnt lgkmcnt(2)
	v_bfe_u32 v23, v68, 16, 1
	v_lshrrev_b32_e32 v4, 16, v4
	v_add3_u32 v23, v68, v23, s42
	v_and_or_b32 v40, v23, s43, v4
	s_waitcnt lgkmcnt(1)
	v_bfe_u32 v4, v70, 16, 1
	s_lshl_b32 s6, s53, 1
	s_lshl_b32 s22, s53, 5
	v_add3_u32 v4, v70, v4, s42
	s_waitcnt lgkmcnt(0)
	v_bfe_u32 v23, v72, 16, 1
	s_add_i32 s6, s6, 0x1ea00
	s_and_b32 s22, s22, 0x3e0
	v_lshrrev_b32_e32 v4, 16, v4
	v_add3_u32 v23, v72, v23, s42
	s_and_b32 s6, s6, 0x1ffc0
	v_and_or_b32 v41, v23, s43, v4
	v_or_b32_e32 v4, s22, v54
	s_lshl_b32 s6, s6, 1
	v_mul_u32_u24_e32 v4, 0xb00, v4
	v_lshl_add_u64 v[44:45], v[34:35], 0, s[6:7]
	v_lshlrev_b32_e32 v4, 1, v4
	v_lshl_add_u64 v[74:75], v[44:45], 0, v[4:5]
	v_bfe_u32 v4, v43, 16, 1
	v_add3_u32 v4, v43, v4, s42
	v_bfe_u32 v23, v47, 16, 1
	v_lshrrev_b32_e32 v4, 16, v4
	v_add3_u32 v23, v47, v23, s42
	global_store_dwordx4 v[74:75], v[38:41], off
	ds_read2_b32 v[42:43], v55 offset0:16 offset1:24
	s_nop 0
	v_and_or_b32 v38, v23, s43, v4
	v_bfe_u32 v4, v49, 16, 1
	v_add3_u32 v4, v49, v4, s42
	v_bfe_u32 v23, v51, 16, 1
	v_lshrrev_b32_e32 v4, 16, v4
	v_add3_u32 v23, v51, v23, s42
	v_and_or_b32 v39, v23, s43, v4
	v_bfe_u32 v4, v53, 16, 1
	v_add3_u32 v4, v53, v4, s42
	v_bfe_u32 v23, v69, 16, 1
	v_lshrrev_b32_e32 v4, 16, v4
	v_add3_u32 v23, v69, v23, s42
	v_and_or_b32 v40, v23, s43, v4
	v_bfe_u32 v4, v71, 16, 1
	v_add3_u32 v4, v71, v4, s42
	v_bfe_u32 v23, v73, 16, 1
	v_lshrrev_b32_e32 v4, 16, v4
	v_add3_u32 v23, v73, v23, s42
	v_and_or_b32 v41, v23, s43, v4
	v_or_b32_e32 v4, s22, v56
	v_mul_u32_u24_e32 v4, 0xb00, v4
	v_lshlrev_b32_e32 v4, 1, v4
	v_lshl_add_u64 v[46:47], v[44:45], 0, v[4:5]
	global_store_dwordx4 v[46:47], v[38:41], off
	ds_read2_b32 v[46:47], v55 offset0:49 offset1:57
	ds_read2_b32 v[48:49], v55 offset0:82 offset1:90
	ds_read2_b32 v[50:51], v55 offset0:115 offset1:123
	s_waitcnt lgkmcnt(3)
	v_bfe_u32 v4, v42, 16, 1
	v_add3_u32 v4, v42, v4, s42
	s_waitcnt lgkmcnt(2)
	v_bfe_u32 v23, v46, 16, 1
	ds_read2_b32 v[52:53], v55 offset0:148 offset1:156
	v_lshrrev_b32_e32 v4, 16, v4
	v_add3_u32 v23, v46, v23, s42
	ds_read2_b32 v[68:69], v55 offset0:181 offset1:189
	v_and_or_b32 v38, v23, s43, v4
	s_waitcnt lgkmcnt(3)
	v_bfe_u32 v4, v48, 16, 1
	v_add3_u32 v4, v48, v4, s42
	s_waitcnt lgkmcnt(2)
	v_bfe_u32 v23, v50, 16, 1
	ds_read2_b32 v[70:71], v55 offset0:214 offset1:222
	v_lshrrev_b32_e32 v4, 16, v4
	v_add3_u32 v23, v50, v23, s42
	ds_read2_b32 v[72:73], v55 offset0:247 offset1:255
	v_and_or_b32 v39, v23, s43, v4
	s_waitcnt lgkmcnt(3)
	v_bfe_u32 v4, v52, 16, 1
	v_add3_u32 v4, v52, v4, s42
	s_waitcnt lgkmcnt(2)
	v_bfe_u32 v23, v68, 16, 1
	v_lshrrev_b32_e32 v4, 16, v4
	v_add3_u32 v23, v68, v23, s42
	v_and_or_b32 v40, v23, s43, v4
	s_waitcnt lgkmcnt(1)
	v_bfe_u32 v4, v70, 16, 1
	v_add3_u32 v4, v70, v4, s42
	s_waitcnt lgkmcnt(0)
	v_bfe_u32 v23, v72, 16, 1
	v_lshrrev_b32_e32 v4, 16, v4
	v_add3_u32 v23, v72, v23, s42
	v_and_or_b32 v41, v23, s43, v4
	v_or_b32_e32 v4, s22, v57
	v_mul_u32_u24_e32 v4, 0xb00, v4
	v_lshlrev_b32_e32 v4, 1, v4
	v_lshl_add_u64 v[74:75], v[44:45], 0, v[4:5]
	v_bfe_u32 v4, v43, 16, 1
	v_add3_u32 v4, v43, v4, s42
	v_bfe_u32 v23, v47, 16, 1
	v_lshrrev_b32_e32 v4, 16, v4
	v_add3_u32 v23, v47, v23, s42
	global_store_dwordx4 v[74:75], v[38:41], off
	s_nop 1
	v_and_or_b32 v38, v23, s43, v4
	v_bfe_u32 v4, v49, 16, 1
	v_add3_u32 v4, v49, v4, s42
	v_bfe_u32 v23, v51, 16, 1
	v_lshrrev_b32_e32 v4, 16, v4
	v_add3_u32 v23, v51, v23, s42
	v_and_or_b32 v39, v23, s43, v4
	v_bfe_u32 v4, v53, 16, 1
	v_add3_u32 v4, v53, v4, s42
	v_bfe_u32 v23, v69, 16, 1
	v_lshrrev_b32_e32 v4, 16, v4
	v_add3_u32 v23, v69, v23, s42
	v_and_or_b32 v40, v23, s43, v4
	v_bfe_u32 v4, v71, 16, 1
	v_add3_u32 v4, v71, v4, s42
	v_bfe_u32 v23, v73, 16, 1
	v_lshrrev_b32_e32 v4, 16, v4
	v_add3_u32 v23, v73, v23, s42
	v_and_or_b32 v41, v23, s43, v4
	v_or_b32_e32 v4, s22, v58
	v_mul_u32_u24_e32 v4, 0xb00, v4
	v_lshlrev_b32_e32 v4, 1, v4
	v_lshl_add_u64 v[42:43], v[44:45], 0, v[4:5]
	global_store_dwordx4 v[42:43], v[38:41], off
	s_waitcnt lgkmcnt(0)

.LBB0_69:
	s_andn2_b64 vcc, exec, s[22:23]
	s_cbranch_vccnz .LBB0_73
	s_add_i32 s6, s53, 0xfa80
	s_and_b32 s22, s6, 0xffff
	s_mul_i32 s22, s22, 0xba2f
	s_lshr_b32 s23, s22, 16
	s_lshr_b32 s22, s22, 22
	s_mulk_i32 s22, 0x58
	s_sub_i32 s6, s6, s22
	s_and_b32 s25, s23, 0xffc0
	s_and_b32 s54, s6, 0xffff
	v_or_b32_e32 v4, s25, v60
	s_lshl_b32 s6, s54, 7
	v_mul_u32_u24_e32 v4, 0x2c00, v4
	v_lshl_add_u64 v[38:39], s[6:7], 0, v[4:5]
	v_or_b32_e32 v4, s25, v61
	v_mul_u32_u24_e32 v4, 0x2c00, v4
	v_lshl_add_u64 v[40:41], s[6:7], 0, v[4:5]
	v_or_b32_e32 v4, s25, v62
	v_mul_u32_u24_e32 v4, 0x2c00, v4
	v_lshl_add_u64 v[42:43], s[6:7], 0, v[4:5]
	v_or_b32_e32 v4, s25, v63
	v_mul_u32_u24_e32 v4, 0x2c00, v4
	v_lshl_add_u64 v[44:45], s[6:7], 0, v[4:5]
	v_or_b32_e32 v4, s25, v64
	v_mul_u32_u24_e32 v4, 0x2c00, v4
	v_lshl_add_u64 v[46:47], s[6:7], 0, v[4:5]
	v_or_b32_e32 v4, s25, v65
	v_mul_u32_u24_e32 v4, 0x2c00, v4
	v_lshl_add_u64 v[48:49], s[6:7], 0, v[4:5]
	v_or_b32_e32 v4, s25, v66
	v_mul_u32_u24_e32 v4, 0x2c00, v4
	v_lshl_add_u64 v[50:51], s[6:7], 0, v[4:5]
	v_or_b32_e32 v4, s25, v3
	v_mov_b64_e32 v[52:53], s[6:7]
	v_mad_u64_u32 v[52:53], s[22:23], v4, s45, v[52:53]
	s_lshl_b32 s24, s54, 5
	v_lshl_add_u64 v[38:39], v[16:17], 0, v[38:39]
	v_lshl_add_u64 v[40:41], v[16:17], 0, v[40:41]
	v_lshl_add_u64 v[42:43], v[16:17], 0, v[42:43]
	v_lshl_add_u64 v[44:45], v[16:17], 0, v[44:45]
	v_lshl_add_u64 v[46:47], v[16:17], 0, v[46:47]
	v_lshl_add_u64 v[48:49], v[16:17], 0, v[48:49]
	v_lshl_add_u64 v[50:51], v[16:17], 0, v[50:51]
	v_lshl_add_u64 v[52:53], v[16:17], 0, v[52:53]
	s_mov_b64 s[22:23], 0
	v_mov_b32_e32 v4, v59
	v_lshl_add_u64 v[68:69], v[52:53], 0, s[22:23]
	v_lshl_add_u64 v[70:71], v[50:51], 0, s[22:23]
	v_lshl_add_u64 v[72:73], v[48:49], 0, s[22:23]
	v_lshl_add_u64 v[74:75], v[46:47], 0, s[22:23]
	v_lshl_add_u64 v[76:77], v[44:45], 0, s[22:23]
	v_lshl_add_u64 v[78:79], v[42:43], 0, s[22:23]
	v_lshl_add_u64 v[80:81], v[40:41], 0, s[22:23]
	v_lshl_add_u64 v[82:83], v[38:39], 0, s[22:23]
	global_load_dword v100, v[68:69], off nt
	s_nop 0
	global_load_dword v101, v[70:71], off nt
	global_load_dword v102, v[72:73], off nt
	s_nop 0
	global_load_dword v103, v[74:75], off nt
	global_load_dword v104, v[76:77], off nt
	global_load_dword v105, v[78:79], off nt
	global_load_dword v106, v[80:81], off nt
	s_nop 0
	global_load_dword v107, v[82:83], off nt
	s_add_u32 s22, s22, 0x2c000
	s_addc_u32 s23, s23, 0
	v_lshl_add_u64 v[68:69], v[52:53], 0, s[22:23]
	v_lshl_add_u64 v[70:71], v[50:51], 0, s[22:23]
	v_lshl_add_u64 v[72:73], v[48:49], 0, s[22:23]
	v_lshl_add_u64 v[74:75], v[46:47], 0, s[22:23]
	v_lshl_add_u64 v[76:77], v[44:45], 0, s[22:23]
	v_lshl_add_u64 v[78:79], v[42:43], 0, s[22:23]
	v_lshl_add_u64 v[80:81], v[40:41], 0, s[22:23]
	v_lshl_add_u64 v[82:83], v[38:39], 0, s[22:23]
	global_load_dword v108, v[68:69], off nt
	s_nop 0
	global_load_dword v109, v[70:71], off nt
	global_load_dword v110, v[72:73], off nt
	s_nop 0
	global_load_dword v111, v[74:75], off nt
	global_load_dword v112, v[76:77], off nt
	global_load_dword v113, v[78:79], off nt
	global_load_dword v114, v[80:81], off nt
	s_nop 0
	global_load_dword v115, v[82:83], off nt
	s_add_u32 s22, s22, 0x2c000
	s_addc_u32 s23, s23, 0
	v_lshl_add_u64 v[68:69], v[52:53], 0, s[22:23]
	v_lshl_add_u64 v[70:71], v[50:51], 0, s[22:23]
	v_lshl_add_u64 v[72:73], v[48:49], 0, s[22:23]
	v_lshl_add_u64 v[74:75], v[46:47], 0, s[22:23]
	v_lshl_add_u64 v[76:77], v[44:45], 0, s[22:23]
	v_lshl_add_u64 v[78:79], v[42:43], 0, s[22:23]
	v_lshl_add_u64 v[80:81], v[40:41], 0, s[22:23]
	v_lshl_add_u64 v[82:83], v[38:39], 0, s[22:23]
	global_load_dword v116, v[68:69], off nt
	s_nop 0
	global_load_dword v117, v[70:71], off nt
	global_load_dword v118, v[72:73], off nt
	s_nop 0
	global_load_dword v119, v[74:75], off nt
	global_load_dword v120, v[76:77], off nt
	global_load_dword v121, v[78:79], off nt
	global_load_dword v122, v[80:81], off nt
	s_nop 0
	global_load_dword v123, v[82:83], off nt
	s_add_u32 s22, s22, 0x2c000
	s_addc_u32 s23, s23, 0
	v_lshl_add_u64 v[68:69], v[52:53], 0, s[22:23]
	v_lshl_add_u64 v[70:71], v[50:51], 0, s[22:23]
	v_lshl_add_u64 v[72:73], v[48:49], 0, s[22:23]
	v_lshl_add_u64 v[74:75], v[46:47], 0, s[22:23]
	v_lshl_add_u64 v[76:77], v[44:45], 0, s[22:23]
	v_lshl_add_u64 v[78:79], v[42:43], 0, s[22:23]
	v_lshl_add_u64 v[80:81], v[40:41], 0, s[22:23]
	v_lshl_add_u64 v[82:83], v[38:39], 0, s[22:23]
	global_load_dword v124, v[68:69], off nt
	s_nop 0
	global_load_dword v125, v[70:71], off nt
	global_load_dword v126, v[72:73], off nt
	s_nop 0
	global_load_dword v127, v[74:75], off nt
	global_load_dword v128, v[76:77], off nt
	global_load_dword v129, v[78:79], off nt
	global_load_dword v130, v[80:81], off nt
	s_nop 0
	global_load_dword v131, v[82:83], off nt
	s_add_u32 s22, s22, 0x2c000
	s_addc_u32 s23, s23, 0
	v_add_u32_e32 v75, 0x400, v4
	s_waitcnt vmcnt(30)
	ds_write2_b32 v4, v100, v101 offset1:66
	s_waitcnt vmcnt(28)
	ds_write2_b32 v4, v102, v103 offset0:132 offset1:198
	s_waitcnt vmcnt(26)
	ds_write2_b32 v75, v104, v105 offset0:8 offset1:74
	s_waitcnt vmcnt(24)
	ds_write2_b32 v75, v106, v107 offset0:140 offset1:206
	v_add_u32_e32 v4, 0x840, v4
	v_add_u32_e32 v75, 0x400, v4
	s_waitcnt vmcnt(22)
	ds_write2_b32 v4, v108, v109 offset1:66
	s_waitcnt vmcnt(20)
	ds_write2_b32 v4, v110, v111 offset0:132 offset1:198
	s_waitcnt vmcnt(18)
	ds_write2_b32 v75, v112, v113 offset0:8 offset1:74
	s_waitcnt vmcnt(16)
	ds_write2_b32 v75, v114, v115 offset0:140 offset1:206
	v_add_u32_e32 v4, 0x840, v4
	v_add_u32_e32 v75, 0x400, v4
	s_waitcnt vmcnt(14)
	ds_write2_b32 v4, v116, v117 offset1:66
	s_waitcnt vmcnt(12)
	ds_write2_b32 v4, v118, v119 offset0:132 offset1:198
	s_waitcnt vmcnt(10)
	ds_write2_b32 v75, v120, v121 offset0:8 offset1:74
	s_waitcnt vmcnt(8)
	ds_write2_b32 v75, v122, v123 offset0:140 offset1:206
	v_add_u32_e32 v4, 0x840, v4
	v_add_u32_e32 v75, 0x400, v4
	s_waitcnt vmcnt(6)
	ds_write2_b32 v4, v124, v125 offset1:66
	s_waitcnt vmcnt(4)
	ds_write2_b32 v4, v126, v127 offset0:132 offset1:198
	s_waitcnt vmcnt(2)
	ds_write2_b32 v75, v128, v129 offset0:8 offset1:74
	s_waitcnt vmcnt(0)
	ds_write2_b32 v75, v130, v131 offset0:140 offset1:206
	v_add_u32_e32 v4, 0x840, v4
	s_waitcnt lgkmcnt(0)
	ds_read2_b32 v[42:43], v55 offset1:8
	ds_read2_b32 v[46:47], v55 offset0:33 offset1:41
	ds_read2_b32 v[48:49], v55 offset0:66 offset1:74
	ds_read2_b32 v[50:51], v55 offset0:99 offset1:107
	ds_read2_b32 v[52:53], v55 offset0:132 offset1:140
	s_waitcnt lgkmcnt(4)
	v_bfe_u32 v4, v42, 16, 1
	v_add3_u32 v4, v42, v4, s42
	s_waitcnt lgkmcnt(3)
	v_bfe_u32 v23, v46, 16, 1
	v_lshrrev_b32_e32 v4, 16, v4
	v_add3_u32 v23, v46, v23, s42
	ds_read2_b32 v[68:69], v55 offset0:165 offset1:173
	v_and_or_b32 v38, v23, s43, v4
	s_waitcnt lgkmcnt(3)
	v_bfe_u32 v4, v48, 16, 1
	v_add3_u32 v4, v48, v4, s42
	s_waitcnt lgkmcnt(2)
	v_bfe_u32 v23, v50, 16, 1
	ds_read2_b32 v[70:71], v55 offset0:198 offset1:206
	v_lshrrev_b32_e32 v4, 16, v4
	v_add3_u32 v23, v50, v23, s42
	ds_read2_b32 v[72:73], v55 offset0:231 offset1:239
	v_and_or_b32 v39, v23, s43, v4
	s_waitcnt lgkmcnt(3)
	v_bfe_u32 v4, v52, 16, 1
	s_lshl_b32 s6, s54, 6
	v_add3_u32 v4, v52, v4, s42
	s_waitcnt lgkmcnt(2)
	v_bfe_u32 v23, v68, 16, 1
	s_and_b32 s6, s6, 0x1f00
	v_lshrrev_b32_e32 v4, 16, v4
	v_add3_u32 v23, v68, v23, s42
	s_or_b32 s22, s6, 0x80
	s_and_b32 s6, 0xffff, s25
	v_and_or_b32 v40, v23, s43, v4
	s_waitcnt lgkmcnt(1)
	v_bfe_u32 v4, v70, 16, 1
	s_lshl_b32 s6, s6, 1
	v_add3_u32 v4, v70, v4, s42
	s_waitcnt lgkmcnt(0)
	v_bfe_u32 v23, v72, 16, 1
	v_lshl_add_u64 v[44:45], v[24:25], 0, s[6:7]
	v_lshrrev_b32_e32 v4, 16, v4
	v_add3_u32 v23, v72, v23, s42
	s_and_b32 s6, s24, 0x60
	v_and_or_b32 v41, v23, s43, v4
	v_or_b32_e32 v4, s6, v54
	v_or_b32_e32 v4, s22, v4
	v_lshlrev_b32_e32 v4, 11, v4
	v_lshl_add_u64 v[74:75], v[44:45], 0, v[4:5]
	v_bfe_u32 v4, v43, 16, 1
	v_add3_u32 v4, v43, v4, s42
	v_bfe_u32 v23, v47, 16, 1
	v_lshrrev_b32_e32 v4, 16, v4
	v_add3_u32 v23, v47, v23, s42
	global_store_dwordx4 v[74:75], v[38:41], off
	ds_read2_b32 v[42:43], v55 offset0:16 offset1:24
	s_nop 0
	v_and_or_b32 v38, v23, s43, v4
	v_bfe_u32 v4, v49, 16, 1
	v_add3_u32 v4, v49, v4, s42
	v_bfe_u32 v23, v51, 16, 1
	v_lshrrev_b32_e32 v4, 16, v4
	v_add3_u32 v23, v51, v23, s42
	v_and_or_b32 v39, v23, s43, v4
	v_bfe_u32 v4, v53, 16, 1
	v_add3_u32 v4, v53, v4, s42
	v_bfe_u32 v23, v69, 16, 1
	v_lshrrev_b32_e32 v4, 16, v4
	v_add3_u32 v23, v69, v23, s42
	v_and_or_b32 v40, v23, s43, v4
	v_bfe_u32 v4, v71, 16, 1
	v_add3_u32 v4, v71, v4, s42
	v_bfe_u32 v23, v73, 16, 1
	v_lshrrev_b32_e32 v4, 16, v4
	v_add3_u32 v23, v73, v23, s42
	v_and_or_b32 v41, v23, s43, v4
	v_or_b32_e32 v4, s6, v56
	v_or_b32_e32 v4, s22, v4
	v_lshlrev_b32_e32 v4, 11, v4
	v_lshl_add_u64 v[46:47], v[44:45], 0, v[4:5]
	global_store_dwordx4 v[46:47], v[38:41], off
	ds_read2_b32 v[46:47], v55 offset0:49 offset1:57
	ds_read2_b32 v[48:49], v55 offset0:82 offset1:90
	ds_read2_b32 v[50:51], v55 offset0:115 offset1:123
	s_waitcnt lgkmcnt(3)
	v_bfe_u32 v4, v42, 16, 1
	v_add3_u32 v4, v42, v4, s42
	s_waitcnt lgkmcnt(2)
	v_bfe_u32 v23, v46, 16, 1
	ds_read2_b32 v[52:53], v55 offset0:148 offset1:156
	v_lshrrev_b32_e32 v4, 16, v4
	v_add3_u32 v23, v46, v23, s42
	ds_read2_b32 v[68:69], v55 offset0:181 offset1:189
	v_and_or_b32 v38, v23, s43, v4
	s_waitcnt lgkmcnt(3)
	v_bfe_u32 v4, v48, 16, 1
	v_add3_u32 v4, v48, v4, s42
	s_waitcnt lgkmcnt(2)
	v_bfe_u32 v23, v50, 16, 1
	ds_read2_b32 v[70:71], v55 offset0:214 offset1:222
	v_lshrrev_b32_e32 v4, 16, v4
	v_add3_u32 v23, v50, v23, s42
	ds_read2_b32 v[72:73], v55 offset0:247 offset1:255
	v_and_or_b32 v39, v23, s43, v4
	s_waitcnt lgkmcnt(3)
	v_bfe_u32 v4, v52, 16, 1
	v_add3_u32 v4, v52, v4, s42
	s_waitcnt lgkmcnt(2)
	v_bfe_u32 v23, v68, 16, 1
	v_lshrrev_b32_e32 v4, 16, v4
	v_add3_u32 v23, v68, v23, s42
	v_and_or_b32 v40, v23, s43, v4
	s_waitcnt lgkmcnt(1)
	v_bfe_u32 v4, v70, 16, 1
	v_add3_u32 v4, v70, v4, s42
	s_waitcnt lgkmcnt(0)
	v_bfe_u32 v23, v72, 16, 1
	v_lshrrev_b32_e32 v4, 16, v4
	v_add3_u32 v23, v72, v23, s42
	v_and_or_b32 v41, v23, s43, v4
	v_or_b32_e32 v4, s6, v57
	v_or_b32_e32 v4, s22, v4
	v_lshlrev_b32_e32 v4, 11, v4
	v_lshl_add_u64 v[74:75], v[44:45], 0, v[4:5]
	v_bfe_u32 v4, v43, 16, 1
	v_add3_u32 v4, v43, v4, s42
	v_bfe_u32 v23, v47, 16, 1
	v_lshrrev_b32_e32 v4, 16, v4
	v_add3_u32 v23, v47, v23, s42
	global_store_dwordx4 v[74:75], v[38:41], off
	s_nop 1
	v_and_or_b32 v38, v23, s43, v4
	v_bfe_u32 v4, v49, 16, 1
	v_add3_u32 v4, v49, v4, s42
	v_bfe_u32 v23, v51, 16, 1
	v_lshrrev_b32_e32 v4, 16, v4
	v_add3_u32 v23, v51, v23, s42
	v_and_or_b32 v39, v23, s43, v4
	v_bfe_u32 v4, v53, 16, 1
	v_add3_u32 v4, v53, v4, s42
	v_bfe_u32 v23, v69, 16, 1
	v_lshrrev_b32_e32 v4, 16, v4
	v_add3_u32 v23, v69, v23, s42
	v_and_or_b32 v40, v23, s43, v4
	v_bfe_u32 v4, v71, 16, 1
	v_add3_u32 v4, v71, v4, s42
	v_bfe_u32 v23, v73, 16, 1
	v_lshrrev_b32_e32 v4, 16, v4
	v_add3_u32 v23, v73, v23, s42
	v_and_or_b32 v41, v23, s43, v4
	v_or_b32_e32 v4, s6, v58
	v_or_b32_e32 v4, s22, v4
	v_lshlrev_b32_e32 v4, 11, v4
	v_lshl_add_u64 v[42:43], v[44:45], 0, v[4:5]
	global_store_dwordx4 v[42:43], v[38:41], off
	s_waitcnt lgkmcnt(0)

.LBB0_74:
	s_andn2_b64 vcc, exec, s[22:23]
	s_cbranch_vccnz .LBB0_33
	s_mul_hi_i32 s6, s53, 0x2e8ba2e9
	s_lshr_b32 s22, s6, 31
	s_ashr_i32 s6, s6, 4
	s_add_i32 s22, s6, s22
	s_mul_i32 s6, s22, 0x58
	s_sub_i32 s6, s53, s6
	s_lshl_b32 s24, s22, 6
	s_lshl_b32 s22, s6, 5
	s_ashr_i32 s23, s22, 31
	v_lshl_add_u64 v[38:39], s[22:23], 2, v[36:37]
	v_or_b32_e32 v4, s24, v3
	s_mov_b32 s23, 0
	v_mov_b32_e32 v23, v59
	v_add_u32_e32 v42, s23, v4
	v_add_u32_e32 v43, 2, v42
	v_add_u32_e32 v44, 4, v42
	v_add_u32_e32 v46, 6, v42
	v_mad_i64_i32 v[40:41], s[54:55], v42, s45, v[38:39]
	v_add_u32_e32 v48, 8, v42
	v_add_u32_e32 v50, 10, v42
	v_add_u32_e32 v52, 12, v42
	v_add_u32_e32 v68, 14, v42
	v_mad_i64_i32 v[42:43], s[54:55], v43, s45, v[38:39]
	v_mad_i64_i32 v[44:45], s[54:55], v44, s45, v[38:39]
	v_mad_i64_i32 v[46:47], s[54:55], v46, s45, v[38:39]
	v_mad_i64_i32 v[48:49], s[54:55], v48, s45, v[38:39]
	v_mad_i64_i32 v[50:51], s[54:55], v50, s45, v[38:39]
	v_mad_i64_i32 v[52:53], s[54:55], v52, s45, v[38:39]
	v_mad_i64_i32 v[68:69], s[54:55], v68, s45, v[38:39]
	global_load_dword v100, v[40:41], off nt
	s_nop 0
	global_load_dword v101, v[42:43], off nt
	s_nop 0
	global_load_dword v102, v[44:45], off nt
	global_load_dword v103, v[46:47], off nt
	s_nop 0
	global_load_dword v104, v[48:49], off nt
	global_load_dword v105, v[50:51], off nt
	global_load_dword v106, v[52:53], off nt
	global_load_dword v107, v[68:69], off nt
	s_add_i32 s23, s23, 16
	v_add_u32_e32 v42, s23, v4
	v_add_u32_e32 v43, 2, v42
	v_add_u32_e32 v44, 4, v42
	v_add_u32_e32 v46, 6, v42
	v_mad_i64_i32 v[40:41], s[54:55], v42, s45, v[38:39]
	v_add_u32_e32 v48, 8, v42
	v_add_u32_e32 v50, 10, v42
	v_add_u32_e32 v52, 12, v42
	v_add_u32_e32 v68, 14, v42
	v_mad_i64_i32 v[42:43], s[54:55], v43, s45, v[38:39]
	v_mad_i64_i32 v[44:45], s[54:55], v44, s45, v[38:39]
	v_mad_i64_i32 v[46:47], s[54:55], v46, s45, v[38:39]
	v_mad_i64_i32 v[48:49], s[54:55], v48, s45, v[38:39]
	v_mad_i64_i32 v[50:51], s[54:55], v50, s45, v[38:39]
	v_mad_i64_i32 v[52:53], s[54:55], v52, s45, v[38:39]
	v_mad_i64_i32 v[68:69], s[54:55], v68, s45, v[38:39]
	global_load_dword v108, v[40:41], off nt
	s_nop 0
	global_load_dword v109, v[42:43], off nt
	s_nop 0
	global_load_dword v110, v[44:45], off nt
	global_load_dword v111, v[46:47], off nt
	s_nop 0
	global_load_dword v112, v[48:49], off nt
	global_load_dword v113, v[50:51], off nt
	global_load_dword v114, v[52:53], off nt
	global_load_dword v115, v[68:69], off nt
	s_add_i32 s23, s23, 16
	v_add_u32_e32 v42, s23, v4
	v_add_u32_e32 v43, 2, v42
	v_add_u32_e32 v44, 4, v42
	v_add_u32_e32 v46, 6, v42
	v_mad_i64_i32 v[40:41], s[54:55], v42, s45, v[38:39]
	v_add_u32_e32 v48, 8, v42
	v_add_u32_e32 v50, 10, v42
	v_add_u32_e32 v52, 12, v42
	v_add_u32_e32 v68, 14, v42
	v_mad_i64_i32 v[42:43], s[54:55], v43, s45, v[38:39]
	v_mad_i64_i32 v[44:45], s[54:55], v44, s45, v[38:39]
	v_mad_i64_i32 v[46:47], s[54:55], v46, s45, v[38:39]
	v_mad_i64_i32 v[48:49], s[54:55], v48, s45, v[38:39]
	v_mad_i64_i32 v[50:51], s[54:55], v50, s45, v[38:39]
	v_mad_i64_i32 v[52:53], s[54:55], v52, s45, v[38:39]
	v_mad_i64_i32 v[68:69], s[54:55], v68, s45, v[38:39]
	global_load_dword v116, v[40:41], off nt
	s_nop 0
	global_load_dword v117, v[42:43], off nt
	s_nop 0
	global_load_dword v118, v[44:45], off nt
	global_load_dword v119, v[46:47], off nt
	s_nop 0
	global_load_dword v120, v[48:49], off nt
	global_load_dword v121, v[50:51], off nt
	global_load_dword v122, v[52:53], off nt
	global_load_dword v123, v[68:69], off nt
	s_add_i32 s23, s23, 16
	v_add_u32_e32 v42, s23, v4
	v_add_u32_e32 v43, 2, v42
	v_add_u32_e32 v44, 4, v42
	v_add_u32_e32 v46, 6, v42
	v_mad_i64_i32 v[40:41], s[54:55], v42, s45, v[38:39]
	v_add_u32_e32 v48, 8, v42
	v_add_u32_e32 v50, 10, v42
	v_add_u32_e32 v52, 12, v42
	v_add_u32_e32 v68, 14, v42
	v_mad_i64_i32 v[42:43], s[54:55], v43, s45, v[38:39]
	v_mad_i64_i32 v[44:45], s[54:55], v44, s45, v[38:39]
	v_mad_i64_i32 v[46:47], s[54:55], v46, s45, v[38:39]
	v_mad_i64_i32 v[48:49], s[54:55], v48, s45, v[38:39]
	v_mad_i64_i32 v[50:51], s[54:55], v50, s45, v[38:39]
	v_mad_i64_i32 v[52:53], s[54:55], v52, s45, v[38:39]
	v_mad_i64_i32 v[68:69], s[54:55], v68, s45, v[38:39]
	global_load_dword v124, v[40:41], off nt
	s_nop 0
	global_load_dword v125, v[42:43], off nt
	s_nop 0
	global_load_dword v126, v[44:45], off nt
	global_load_dword v127, v[46:47], off nt
	s_nop 0
	global_load_dword v128, v[48:49], off nt
	global_load_dword v129, v[50:51], off nt
	global_load_dword v130, v[52:53], off nt
	global_load_dword v131, v[68:69], off nt
	s_add_i32 s23, s23, 16
	v_add_u32_e32 v48, 0x400, v23
	s_waitcnt vmcnt(30)
	ds_write2_b32 v23, v100, v101 offset1:66
	s_waitcnt vmcnt(28)
	ds_write2_b32 v23, v102, v103 offset0:132 offset1:198
	s_waitcnt vmcnt(26)
	ds_write2_b32 v48, v104, v105 offset0:8 offset1:74
	s_waitcnt vmcnt(24)
	ds_write2_b32 v48, v106, v107 offset0:140 offset1:206
	v_add_u32_e32 v23, 0x840, v23
	v_add_u32_e32 v48, 0x400, v23
	s_waitcnt vmcnt(22)
	ds_write2_b32 v23, v108, v109 offset1:66
	s_waitcnt vmcnt(20)
	ds_write2_b32 v23, v110, v111 offset0:132 offset1:198
	s_waitcnt vmcnt(18)
	ds_write2_b32 v48, v112, v113 offset0:8 offset1:74
	s_waitcnt vmcnt(16)
	ds_write2_b32 v48, v114, v115 offset0:140 offset1:206
	v_add_u32_e32 v23, 0x840, v23
	v_add_u32_e32 v48, 0x400, v23
	s_waitcnt vmcnt(14)
	ds_write2_b32 v23, v116, v117 offset1:66
	s_waitcnt vmcnt(12)
	ds_write2_b32 v23, v118, v119 offset0:132 offset1:198
	s_waitcnt vmcnt(10)
	ds_write2_b32 v48, v120, v121 offset0:8 offset1:74
	s_waitcnt vmcnt(8)
	ds_write2_b32 v48, v122, v123 offset0:140 offset1:206
	v_add_u32_e32 v23, 0x840, v23
	v_add_u32_e32 v48, 0x400, v23
	s_waitcnt vmcnt(6)
	ds_write2_b32 v23, v124, v125 offset1:66
	s_waitcnt vmcnt(4)
	ds_write2_b32 v23, v126, v127 offset0:132 offset1:198
	s_waitcnt vmcnt(2)
	ds_write2_b32 v48, v128, v129 offset0:8 offset1:74
	s_waitcnt vmcnt(0)
	ds_write2_b32 v48, v130, v131 offset0:140 offset1:206
	v_add_u32_e32 v23, 0x840, v23
	s_waitcnt lgkmcnt(0)
	ds_read2_b32 v[42:43], v55 offset1:8
	ds_read2_b32 v[46:47], v55 offset0:33 offset1:41
	ds_read2_b32 v[48:49], v55 offset0:66 offset1:74
	ds_read2_b32 v[50:51], v55 offset0:99 offset1:107
	ds_read2_b32 v[52:53], v55 offset0:132 offset1:140
	s_waitcnt lgkmcnt(4)
	v_bfe_u32 v4, v42, 16, 1
	v_add3_u32 v4, v42, v4, s42
	s_waitcnt lgkmcnt(3)
	v_bfe_u32 v23, v46, 16, 1
	v_lshrrev_b32_e32 v4, 16, v4
	v_add3_u32 v23, v46, v23, s42
	ds_read2_b32 v[68:69], v55 offset0:165 offset1:173
	v_and_or_b32 v38, v23, s43, v4
	s_waitcnt lgkmcnt(3)
	v_bfe_u32 v4, v48, 16, 1
	v_add3_u32 v4, v48, v4, s42
	s_waitcnt lgkmcnt(2)
	v_bfe_u32 v23, v50, 16, 1
	ds_read2_b32 v[70:71], v55 offset0:198 offset1:206
	v_lshrrev_b32_e32 v4, 16, v4
	v_add3_u32 v23, v50, v23, s42
	ds_read2_b32 v[72:73], v55 offset0:231 offset1:239
	v_and_or_b32 v39, v23, s43, v4
	s_waitcnt lgkmcnt(3)
	v_bfe_u32 v4, v52, 16, 1
	v_add3_u32 v4, v52, v4, s42
	s_waitcnt lgkmcnt(2)
	v_bfe_u32 v23, v68, 16, 1
	s_lshl_b32 s6, s6, 6
	v_lshrrev_b32_e32 v4, 16, v4
	v_add3_u32 v23, v68, v23, s42
	s_and_b32 s6, s6, 0xffffff00
	v_and_or_b32 v40, v23, s43, v4
	s_waitcnt lgkmcnt(1)
	v_bfe_u32 v4, v70, 16, 1
	s_and_b32 s22, s22, 0x60
	v_add3_u32 v4, v70, v4, s42
	s_waitcnt lgkmcnt(0)
	v_bfe_u32 v23, v72, 16, 1
	s_or_b32 s6, s6, s22
	v_lshrrev_b32_e32 v4, 16, v4
	v_add3_u32 v23, v72, v23, s42
	v_or_b32_e32 v74, s6, v54
	s_ashr_i32 s25, s24, 31
	v_and_or_b32 v41, v23, s43, v4
	v_ashrrev_i32_e32 v75, 31, v74
	v_bfe_u32 v4, v43, 16, 1
	v_lshl_add_u64 v[44:45], s[24:25], 1, v[24:25]
	v_lshlrev_b64 v[74:75], 11, v[74:75]
	v_add3_u32 v4, v43, v4, s42
	v_bfe_u32 v23, v47, 16, 1
	v_lshl_add_u64 v[74:75], v[44:45], 0, v[74:75]
	v_lshrrev_b32_e32 v4, 16, v4
	v_add3_u32 v23, v47, v23, s42
	global_store_dwordx4 v[74:75], v[38:41], off
	v_or_b32_e32 v42, s6, v56
	v_ashrrev_i32_e32 v43, 31, v42
	v_and_or_b32 v38, v23, s43, v4
	v_bfe_u32 v4, v49, 16, 1
	v_add3_u32 v4, v49, v4, s42
	v_bfe_u32 v23, v51, 16, 1
	v_lshrrev_b32_e32 v4, 16, v4
	v_add3_u32 v23, v51, v23, s42
	v_and_or_b32 v39, v23, s43, v4
	v_bfe_u32 v4, v53, 16, 1
	v_add3_u32 v4, v53, v4, s42
	v_bfe_u32 v23, v69, 16, 1
	v_lshrrev_b32_e32 v4, 16, v4
	v_add3_u32 v23, v69, v23, s42
	v_and_or_b32 v40, v23, s43, v4
	v_bfe_u32 v4, v71, 16, 1
	v_add3_u32 v4, v71, v4, s42
	v_bfe_u32 v23, v73, 16, 1
	v_lshrrev_b32_e32 v4, 16, v4
	v_add3_u32 v23, v73, v23, s42
	v_lshlrev_b64 v[42:43], 11, v[42:43]
	v_and_or_b32 v41, v23, s43, v4
	ds_read2_b32 v[46:47], v55 offset0:16 offset1:24
	v_lshl_add_u64 v[42:43], v[44:45], 0, v[42:43]
	global_store_dwordx4 v[42:43], v[38:41], off
	ds_read2_b32 v[42:43], v55 offset0:49 offset1:57
	ds_read2_b32 v[48:49], v55 offset0:82 offset1:90
	ds_read2_b32 v[50:51], v55 offset0:115 offset1:123
	s_waitcnt lgkmcnt(3)
	v_bfe_u32 v4, v46, 16, 1
	v_add3_u32 v4, v46, v4, s42
	s_waitcnt lgkmcnt(2)
	v_bfe_u32 v23, v42, 16, 1
	ds_read2_b32 v[52:53], v55 offset0:148 offset1:156
	v_lshrrev_b32_e32 v4, 16, v4
	v_add3_u32 v23, v42, v23, s42
	ds_read2_b32 v[68:69], v55 offset0:181 offset1:189
	v_and_or_b32 v38, v23, s43, v4
	s_waitcnt lgkmcnt(3)
	v_bfe_u32 v4, v48, 16, 1
	v_add3_u32 v4, v48, v4, s42
	s_waitcnt lgkmcnt(2)
	v_bfe_u32 v23, v50, 16, 1
	ds_read2_b32 v[70:71], v55 offset0:214 offset1:222
	v_lshrrev_b32_e32 v4, 16, v4
	v_add3_u32 v23, v50, v23, s42
	ds_read2_b32 v[72:73], v55 offset0:247 offset1:255
	v_and_or_b32 v39, v23, s43, v4
	s_waitcnt lgkmcnt(3)
	v_bfe_u32 v4, v52, 16, 1
	v_add3_u32 v4, v52, v4, s42
	s_waitcnt lgkmcnt(2)
	v_bfe_u32 v23, v68, 16, 1
	v_lshrrev_b32_e32 v4, 16, v4
	v_add3_u32 v23, v68, v23, s42
	v_and_or_b32 v40, v23, s43, v4
	s_waitcnt lgkmcnt(1)
	v_bfe_u32 v4, v70, 16, 1
	v_add3_u32 v4, v70, v4, s42
	s_waitcnt lgkmcnt(0)
	v_bfe_u32 v23, v72, 16, 1
	v_lshrrev_b32_e32 v4, 16, v4
	v_add3_u32 v23, v72, v23, s42
	v_or_b32_e32 v74, s6, v57
	v_and_or_b32 v41, v23, s43, v4
	v_ashrrev_i32_e32 v75, 31, v74
	v_bfe_u32 v4, v47, 16, 1
	v_lshlrev_b64 v[74:75], 11, v[74:75]
	v_add3_u32 v4, v47, v4, s42
	v_bfe_u32 v23, v43, 16, 1
	v_lshl_add_u64 v[74:75], v[44:45], 0, v[74:75]
	v_lshrrev_b32_e32 v4, 16, v4
	v_add3_u32 v23, v43, v23, s42
	global_store_dwordx4 v[74:75], v[38:41], off
	v_or_b32_e32 v42, s6, v58
	v_ashrrev_i32_e32 v43, 31, v42
	v_and_or_b32 v38, v23, s43, v4
	v_bfe_u32 v4, v49, 16, 1
	v_add3_u32 v4, v49, v4, s42
	v_bfe_u32 v23, v51, 16, 1
	v_lshrrev_b32_e32 v4, 16, v4
	v_add3_u32 v23, v51, v23, s42
	v_and_or_b32 v39, v23, s43, v4
	v_bfe_u32 v4, v53, 16, 1
	v_add3_u32 v4, v53, v4, s42
	v_bfe_u32 v23, v69, 16, 1
	v_lshrrev_b32_e32 v4, 16, v4
	v_add3_u32 v23, v69, v23, s42
	v_and_or_b32 v40, v23, s43, v4
	v_bfe_u32 v4, v71, 16, 1
	v_add3_u32 v4, v71, v4, s42
	v_bfe_u32 v23, v73, 16, 1
	v_lshrrev_b32_e32 v4, 16, v4
	v_add3_u32 v23, v73, v23, s42
	v_lshlrev_b64 v[42:43], 11, v[42:43]
	v_and_or_b32 v41, v23, s43, v4
	v_lshl_add_u64 v[42:43], v[44:45], 0, v[42:43]
	global_store_dwordx4 v[42:43], v[38:41], off
	s_waitcnt lgkmcnt(0)
	s_branch .LBB0_33
